# nt hint on the attention phase's single-use Q and gate loads, on top of the other streaming-load nt hints
# baseline (speedup 1.0000x reference)
.LBB0_1234:
	s_bfe_u32 s93, s3, 0x30007
	s_bfe_u32 s26, s3, 0x30004
	s_and_b32 s27, s3, 15
	s_cmpk_gt_u32 s3, 0x3ff
	s_mov_b64 s[4:5], -1
	s_cbranch_scc0 .LBB0_1310
	s_getreg_b32 s4, hwreg(HW_REG_HW_ID, 0, 6)
	s_lshl_b32 s4, s4, 2
	s_and_b32 s4, s4, 0xfc
	s_add_i32 s4, s4, 0
	s_add_i32 s4, s4, 0x256c0
	v_mov_b32_e32 v0, s4
	ds_read_b32 v0, v0
	v_mbcnt_lo_u32_b32 v116, -1, 0
	v_mbcnt_hi_u32_b32 v116, -1, v116
	s_lshl_b32 s4, s27, 8
	v_and_b32_e32 v237, 31, v116
	s_mul_i32 s7, s26, 0xc0
	s_waitcnt lgkmcnt(0)
	v_readfirstlane_b32 s5, v0
	v_bfe_u32 v238, v116, 5, 1
	v_lshlrev_b32_e32 v234, 4, v238
	v_lshl_add_u32 v0, s5, 6, v116
	s_lshl_b32 s5, s93, 12
	v_readfirstlane_b32 s20, v0
	s_ashr_i32 s95, s20, 6
	s_or_b32 s94, s5, s4
	s_lshl_b32 s4, s95, 5
	s_add_i32 s94, s94, s4
	s_mul_i32 s5, s94, 0x600
	s_mul_hi_i32 s4, s94, 0x600
	s_add_u32 s5, s85, s5
	s_addc_u32 s6, s86, s4
	s_add_u32 s4, s5, s7
	v_mul_u32_u24_e32 v0, 0x300, v237
	s_addc_u32 s5, s6, 0
	v_lshlrev_b32_e32 v0, 1, v0
	v_lshl_add_u64 v[2:3], s[4:5], 0, v[0:1]
	v_mov_b32_e32 v235, v1
	v_lshl_add_u64 v[2:3], v[2:3], 0, v[234:235]
	global_load_dwordx4 v[180:183], v[2:3], off nt
	global_load_dwordx4 v[176:179], v[2:3], off offset:32 nt
	global_load_dwordx4 v[172:175], v[2:3], off offset:64 nt
	global_load_dwordx4 v[168:171], v[2:3], off offset:96 nt
	global_load_dwordx4 v[164:167], v[2:3], off offset:128 nt
	global_load_dwordx4 v[160:163], v[2:3], off offset:160 nt
	s_ashr_i32 s5, s20, 8
	s_and_b32 s4, s95, 3
	s_lshl_b32 s60, s5, 5
	s_lshl_b32 s42, s4, 4
	s_ashr_i32 s61, s60, 31
	s_lshl_b32 s5, s5, 12
	s_cmp_lg_u32 0, -1
	s_cselect_b32 s6, 0, 0
	s_lshl_b32 s44, s4, 10
	s_add_i32 s67, s6, s44
	s_mul_i32 s21, s93, 0x660000
	s_add_i32 s47, s67, s5
	v_lshrrev_b32_e32 v0, 4, v116
	s_add_u32 s4, s87, s21
	v_xor_b32_e32 v0, v0, v116
	s_addc_u32 s5, s88, 0
	v_lshlrev_b32_e32 v0, 3, v0
	s_add_u32 s4, s4, s7
	v_bfe_u32 v118, v116, 2, 4
	v_and_b32_e32 v117, 24, v0
	s_addc_u32 s5, s5, 0
	v_or_b32_e32 v80, s42, v118
	v_or_b32_e32 v2, s60, v117
	v_mov_b64_e32 v[4:5], s[4:5]
	s_movk_i32 s4, 0x600
	v_ashrrev_i32_e32 v3, 31, v2
	v_mad_u64_u32 v[4:5], s[4:5], v80, s4, v[4:5]
	s_addk_i32 s67, 0x2000
	v_lshl_add_u64 v[224:225], v[2:3], 1, v[4:5]
	s_mov_b32 s4, m0
	s_mov_b32 m0, s47
	s_nop 0
	global_load_lds_dwordx4 v[224:225], off
	s_mov_b32 m0, s4
	s_cmp_lt_i32 s95, 4
	s_cselect_b64 s[4:5], -1, 0
	s_cmp_gt_i32 s95, 3
	s_cselect_b64 s[28:29], -1, 0
	s_and_b64 vcc, exec, s[28:29]
	s_cbranch_vccnz .LBB0_1237
	s_lshl_b64 s[6:7], s[60:61], 1
	v_mov_b32_e32 v0, s7
	v_subrev_co_u32_e32 v2, vcc, s6, v224
	s_nop 1
	v_subb_co_u32_e32 v3, vcc, v225, v0, vcc
	v_lshl_add_u64 v[2:3], v[2:3], 0, s[10:11]
	s_mov_b32 s6, m0
	s_mov_b32 m0, s67
	s_nop 0
	global_load_lds_dwordx4 v[2:3], off
	s_mov_b32 m0, s6

.LBB0_1304:
	v_lshrrev_b32_e32 v224, 3, v246
	v_or_b32_e32 v2, s94, v224
	v_mov_b32_e32 v3, s96
	v_lshlrev_b64 v[14:15], 11, v[2:3]
	v_lshl_add_u64 v[2:3], s[48:49], 0, v[14:15]
	s_lshl_b32 s8, s8, 1
	v_and_b32_e32 v0, 56, v243
	v_lshl_add_u64 v[2:3], v[2:3], 0, s[8:9]
	v_lshlrev_b32_e32 v0, 1, v0
	v_lshl_add_u64 v[2:3], v[2:3], 0, v[0:1]
	v_add_co_u32_e32 v6, vcc, s67, v2
	s_nop 1
	v_addc_co_u32_e32 v7, vcc, 0, v3, vcc
	global_load_dwordx4 v[140:143], v[2:3], off offset:1024 nt
	global_load_dwordx4 v[136:139], v[6:7], off offset:1024 nt
	v_add_co_u32_e32 v6, vcc, s66, v2
	s_nop 1
	v_addc_co_u32_e32 v7, vcc, 0, v3, vcc
	v_add_co_u32_e32 v2, vcc, s63, v2
	s_nop 1
	v_addc_co_u32_e32 v3, vcc, 0, v3, vcc
	global_load_dwordx4 v[132:135], v[6:7], off offset:1024 nt
	global_load_dwordx4 v[128:131], v[2:3], off offset:1024 nt
	ds_read_b64_tr_b16 v[156:157], v248 offset:16384
	ds_read_b64_tr_b16 v[158:159], v248 offset:16896
	s_waitcnt lgkmcnt(13)
	v_mfma_f32_32x32x16_bf16 v[96:111], v[220:223], v[180:183], v[64:79]
	v_add_f32_e32 v250, v112, v113
	v_add_f32_e32 v251, v114, v115
	v_add_f32_e32 v252, v116, v117
	v_add_f32_e32 v253, v118, v119
	v_add_f32_e32 v250, v120, v250
	v_cvt_pk_bf16_f32 v184, v112, v113
	v_cvt_pk_bf16_f32 v185, v114, v115
	ds_read_b64_tr_b16 v[112:113], v248 offset:20480
	ds_read_b64_tr_b16 v[114:115], v248 offset:20992
	s_waitcnt lgkmcnt(14)
	v_mfma_f32_32x32x16_bf16 v[64:79], v[216:219], v[180:183], v[64:79]
	v_add_f32_e32 v251, v121, v251
	v_add_f32_e32 v252, v122, v252
	v_add_f32_e32 v253, v123, v253
	v_add_f32_e32 v250, v124, v250
	v_cvt_pk_bf16_f32 v186, v116, v117
	v_cvt_pk_bf16_f32 v187, v118, v119
	ds_read_b64_tr_b16 v[116:117], v248 offset:17408
	ds_read_b64_tr_b16 v[118:119], v248 offset:17920
	s_waitcnt lgkmcnt(14)
	v_mfma_f32_32x32x16_bf16 v[96:111], v[212:215], v[176:179], v[96:111]
	v_add_f32_e32 v251, v125, v251
	v_add_f32_e32 v252, v126, v252
	v_add_f32_e32 v253, v127, v253
	v_add_f32_e32 v250, v80, v250
	v_cvt_pk_bf16_f32 v10, v120, v121
	v_cvt_pk_bf16_f32 v11, v122, v123
	ds_read_b64_tr_b16 v[120:121], v248 offset:21504
	ds_read_b64_tr_b16 v[122:123], v248 offset:22016
	v_mfma_f32_32x32x16_bf16 v[64:79], v[208:211], v[176:179], v[64:79]
	v_add_f32_e32 v251, v81, v251
	v_add_f32_e32 v252, v82, v252
	v_add_f32_e32 v253, v83, v253
	v_add_f32_e32 v250, v84, v250
	v_cvt_pk_bf16_f32 v12, v124, v125
	v_cvt_pk_bf16_f32 v13, v126, v127
	ds_read_b64_tr_b16 v[124:125], v248 offset:18432
	ds_read_b64_tr_b16 v[126:127], v248 offset:18944
	s_waitcnt lgkmcnt(14)
	v_mfma_f32_32x32x16_bf16 v[96:111], v[204:207], v[172:175], v[96:111]
	v_add_f32_e32 v251, v85, v251
	v_add_f32_e32 v252, v86, v252
	v_add_f32_e32 v253, v87, v253
	v_add_f32_e32 v250, v88, v250
	v_cvt_pk_bf16_f32 v6, v80, v81
	v_cvt_pk_bf16_f32 v7, v82, v83
	ds_read_b64_tr_b16 v[176:177], v248 offset:22528
	ds_read_b64_tr_b16 v[178:179], v248 offset:23040
	v_mfma_f32_32x32x16_bf16 v[64:79], v[192:195], v[172:175], v[64:79]
	v_add_f32_e32 v251, v89, v251
	v_add_f32_e32 v252, v90, v252
	v_add_f32_e32 v253, v91, v253
	v_add_f32_e32 v250, v92, v250
	v_cvt_pk_bf16_f32 v8, v84, v85
	v_cvt_pk_bf16_f32 v9, v86, v87
	ds_read_b64_tr_b16 v[172:173], v248 offset:19456
	ds_read_b64_tr_b16 v[174:175], v248 offset:19968
	v_mfma_f32_32x32x16_bf16 v[96:111], v[188:191], v[168:171], v[96:111]
	v_add_f32_e32 v251, v93, v251
	v_add_f32_e32 v252, v94, v252
	v_add_f32_e32 v253, v95, v253
	v_add_f32_e32 v250, v251, v250
	v_cvt_pk_bf16_f32 v2, v88, v89
	v_cvt_pk_bf16_f32 v3, v90, v91
	ds_read_b64_tr_b16 v[180:181], v248 offset:23552
	ds_read_b64_tr_b16 v[182:183], v248 offset:24064
	v_mfma_f32_32x32x16_bf16 v[64:79], v[144:147], v[168:171], v[64:79]
	v_add_f32_e32 v252, v253, v252
	v_add_f32_e32 v80, v252, v250
	v_cvt_pk_bf16_f32 v4, v92, v93
	v_cvt_pk_bf16_f32 v5, v94, v95
	s_waitcnt lgkmcnt(14)
	v_mfma_f32_32x32x16_bf16 v[96:111], v[152:155], v[164:167], v[96:111]
	v_mfma_f32_32x32x16_bf16 v[64:79], v[148:151], v[164:167], v[64:79]
	v_mfma_f32_32x32x16_bf16 v[96:111], v[200:203], v[160:163], v[96:111]
	v_mfma_f32_32x32x16_bf16 v[64:79], v[196:199], v[160:163], v[64:79]
	s_nop 10
	v_max_f32_e32 v81, v96, v96
	v_max_f32_e32 v81, 0xff800000, v81
	v_max3_f32 v82, v98, s69, v99
	v_max3_f32 v81, v81, v97, v64
	v_max3_f32 v82, v82, v66, v67
	v_max3_f32 v81, v81, v65, v100
	v_max3_f32 v82, v82, v102, v103
	v_max3_f32 v81, v81, v101, v68
	v_max3_f32 v82, v82, v70, v71
	v_max3_f32 v81, v81, v69, v104
	v_max3_f32 v82, v82, v106, v107
	v_max3_f32 v81, v81, v105, v72
	v_max3_f32 v82, v82, v74, v75
	v_max3_f32 v81, v81, v73, v108
	v_max3_f32 v82, v82, v110, v111
	v_max3_f32 v81, v81, v109, v76
	v_max3_f32 v82, v82, v78, v79
	v_add_f32_e32 v144, v225, v80
	v_max3_f32 v80, v81, v77, v82
	v_mov_b32_e32 v81, v80
	s_nop 1
	v_permlane32_swap_b32_e32 v80, v81
	v_max3_f32 v80, v80, s69, v81
	v_cmp_lt_f32_e32 vcc, s72, v80
	s_cmp_lg_u64 vcc, 0
	s_cselect_b64 s[6:7], -1, 0
	s_cbranch_vccnz .LBB0_1368

.LBB0_1310:
	s_and_b64 vcc, exec, s[4:5]
	s_cbranch_vccz .LBB0_1233
	s_lshr_b32 s4, s3, 7
	s_lshl_b32 s5, s3, 1
	s_and_b32 s30, s5, 0x80
	s_lshl_b32 s5, s27, 8
	s_lshl_b32 s4, s4, 12
	s_mul_i32 s93, s93, 0x110000
	s_lshl_b32 s26, s26, 6
	s_and_b32 s28, s3, 64
	s_or_b32 s29, s4, s5
	s_andn2_b64 vcc, exec, s[0:1]
	s_mov_b64 s[4:5], -1
	s_cbranch_vccnz .LBB0_1317
	s_getreg_b32 s4, hwreg(HW_REG_HW_ID, 0, 6)
	s_lshl_b32 s4, s4, 2
	s_and_b32 s4, s4, 0xfc
	s_add_i32 s4, s4, 0
	s_add_i32 s4, s4, 0x256c0
	v_mov_b32_e32 v0, s4
	ds_read_b32 v0, v0
	v_mbcnt_lo_u32_b32 v116, -1, 0
	v_mbcnt_hi_u32_b32 v116, -1, v116
	v_readlane_b32 s8, v254, 8
	v_and_b32_e32 v200, 31, v116
	v_bfe_u32 v201, v116, 5, 1
	s_waitcnt lgkmcnt(0)
	v_readfirstlane_b32 s4, v0
	v_lshlrev_b32_e32 v2, 10, v200
	v_mov_b32_e32 v3, v1
	v_lshl_add_u32 v0, s4, 6, v116
	v_lshlrev_b32_e32 v4, 4, v201
	v_readfirstlane_b32 s21, v0
	s_ashr_i32 s27, s21, 6
	s_lshl_b32 s4, s27, 5
	s_add_i32 s4, s4, s29
	s_ashr_i32 s5, s4, 31
	s_lshl_b64 s[6:7], s[4:5], 10
	s_add_u32 s6, s8, s6
	v_readlane_b32 s8, v254, 35
	s_addc_u32 s7, s8, s7
	s_lshl_b32 s8, s26, 1
	s_add_u32 s6, s6, s8
	s_addc_u32 s7, s7, 0
	v_lshl_add_u64 v[2:3], s[6:7], 0, v[2:3]
	v_mov_b32_e32 v5, v1
	v_lshl_add_u64 v[2:3], v[2:3], 0, v[4:5]
	global_load_dwordx4 v[172:175], v[2:3], off nt
	global_load_dwordx4 v[176:179], v[2:3], off offset:32 nt
	global_load_dwordx4 v[168:171], v[2:3], off offset:64 nt
	global_load_dwordx4 v[164:167], v[2:3], off offset:96 nt
	v_readlane_b32 s6, v254, 33
	s_add_u32 s6, s6, s93
	s_addc_u32 s7, s82, 0
	s_lshl_b32 s20, s28, 1
	s_add_u32 s6, s6, s20
	v_lshrrev_b32_e32 v0, 4, v116
	v_lshlrev_b32_e32 v4, 6, v116
	s_addc_u32 s7, s7, 0
	s_ashr_i32 s43, s21, 8
	v_lshrrev_b32_e32 v6, 2, v116
	v_xor_b32_e32 v0, v0, v116
	v_and_b32_e32 v7, 0xf00, v4
	s_and_b32 s31, s27, 3
	s_lshl_b32 s42, s43, 5
	v_bitop3_b32 v4, v201, v6, 3 bitop3:0x78
	v_lshlrev_b32_e32 v6, 3, v0
	s_lshl_b32 s8, s27, 10
	v_lshl_or_b32 v0, s31, 12, v7
	s_lshl_b32 s46, s43, 12
	s_lshl_b32 s31, s31, 10
	s_ashr_i32 s43, s42, 31
	v_lshl_add_u64 v[2:3], s[6:7], 0, v[0:1]
	s_add_u32 s6, s83, s93
	s_addc_u32 s7, s84, 0
	s_add_u32 s44, s6, s20
	s_addc_u32 s45, s7, 0
	s_lshl_b64 s[6:7], s[42:43], 1
	v_and_or_b32 v6, v6, 24, s42
	s_cmp_lg_u32 0, -1
	v_lshlrev_b32_e32 v207, 3, v116
	v_ashrrev_i32_e32 v7, 31, v6
	s_cselect_b32 s20, 0, 0
	v_and_b32_e32 v202, 24, v207
	v_lshlrev_b64 v[10:11], 1, v[6:7]
	v_lshl_add_u64 v[12:13], s[44:45], 0, v[0:1]
	s_add_i32 s42, s46, s20
	v_lshlrev_b32_e32 v49, 4, v4
	v_lshlrev_b32_e32 v4, 1, v202
	v_lshl_add_u64 v[192:193], v[2:3], 0, v[10:11]
	v_lshl_add_u64 v[12:13], v[12:13], 0, s[6:7]
	s_add_i32 s60, s20, s8
	s_add_i32 s31, s42, s31
	s_mov_b32 s20, m0
	s_mov_b32 m0, s31
	s_nop 0
	global_load_lds_dwordx4 v[192:193], off
	s_mov_b32 m0, s20
	s_mov_b64 s[94:95], 0x4000
	v_lshl_add_u64 v[14:15], v[12:13], 0, v[4:5]
	s_add_i32 s42, s60, 0x8000
	s_mov_b32 s46, m0
	s_mov_b32 m0, s42
	s_nop 0
	global_load_lds_dwordx4 v[14:15], off
	s_mov_b32 m0, s46
	v_lshl_add_u64 v[2:3], v[192:193], 0, s[94:95]
	s_add_i32 s44, s31, 0x2000
	s_mov_b32 s46, m0
	s_mov_b32 m0, s44
	s_nop 0
	global_load_lds_dwordx4 v[2:3], off
	s_mov_b32 m0, s46
	v_mov_b64_e32 v[46:47], v[30:31]
	v_lshl_add_u64 v[4:5], v[14:15], 0, s[94:95]
	s_add_i32 s43, s60, 0xa000
	s_mov_b32 s44, m0
	s_mov_b32 m0, s43
	s_nop 0
	global_load_lds_dwordx4 v[4:5], off
	s_mov_b32 m0, s44
	v_mov_b64_e32 v[44:45], v[28:29]
	v_mov_b64_e32 v[42:43], v[26:27]
	v_mov_b64_e32 v[40:41], v[24:25]
	v_mov_b64_e32 v[38:39], v[22:23]
	v_mov_b64_e32 v[36:37], v[20:21]
	v_mov_b64_e32 v[34:35], v[18:19]
	v_mov_b64_e32 v[32:33], v[16:17]
	v_lshl_add_u32 v48, v200, 6, 0
	v_lshl_add_u64 v[6:7], v[192:193], 0, s[22:23]
	s_add_i32 s45, s31, 0x4000
	s_mov_b32 s43, m0
	s_mov_b32 m0, s45
	s_nop 0
	global_load_lds_dwordx4 v[6:7], off
	s_mov_b32 m0, s43
	v_add_u32_e32 v208, v48, v49
	v_lshl_add_u64 v[8:9], v[192:193], 0, s[24:25]
	s_add_i32 s20, s31, 0x6000
	s_mov_b32 s43, m0
	s_mov_b32 m0, s20
	s_nop 0
	global_load_lds_dwordx4 v[8:9], off
	s_mov_b32 m0, s43
	s_waitcnt vmcnt(5) lgkmcnt(0)
	s_barrier
	ds_read_b128 v[2:5], v208
	ds_read_b128 v[6:9], v208 offset:2048
	s_waitcnt vmcnt(3) lgkmcnt(1)
	v_mfma_f32_32x32x16_bf16 v[64:79], v[2:5], v[172:175], v[32:47]
	v_xad_u32 v209, v49, 32, v48
	s_add_i32 s60, s60, 0xc000
	s_mov_b32 s43, -1
	s_mov_b32 s46, 0
	s_movk_i32 s47, 0x2000
	s_movk_i32 s44, 0x4000
	s_movk_i32 s45, 0x6000
	s_waitcnt lgkmcnt(0)
	v_mfma_f32_32x32x16_bf16 v[48:63], v[6:9], v[172:175], v[32:47]
	ds_read_b128 v[2:5], v209
	ds_read_b128 v[6:9], v209 offset:2048
	v_and_b32_e32 v203, 63, v116
	v_lshl_add_u64 v[194:195], v[14:15], 0, s[24:25]
	s_waitcnt vmcnt(2) lgkmcnt(1)
	v_mfma_f32_32x32x16_bf16 v[64:79], v[2:5], v[176:179], v[64:79]
	s_waitcnt lgkmcnt(0)
	v_mfma_f32_32x32x16_bf16 v[48:63], v[6:9], v[176:179], v[48:63]
	ds_read_b128 v[2:5], v208 offset:4096
	ds_read_b128 v[6:9], v208 offset:6144
	s_waitcnt vmcnt(1) lgkmcnt(1)
	v_mfma_f32_32x32x16_bf16 v[64:79], v[2:5], v[168:171], v[64:79]
	ds_read_b128 v[2:5], v209 offset:4096
	s_waitcnt lgkmcnt(1)
	v_mfma_f32_32x32x16_bf16 v[48:63], v[6:9], v[168:171], v[48:63]
	ds_read_b128 v[6:9], v209 offset:6144
	s_waitcnt vmcnt(3) lgkmcnt(0)
	s_barrier
	s_waitcnt vmcnt(0) lgkmcnt(1)
	v_mfma_f32_32x32x16_bf16 v[64:79], v[2:5], v[164:167], v[64:79]
	v_lshlrev_b32_e32 v2, 1, v116
	v_lshlrev_b32_e32 v3, 4, v116
	v_and_b32_e32 v204, 32, v2
	v_and_b32_e32 v2, 0xc0, v3
	v_lshl_or_b32 v205, v201, 8, v2
	v_lshl_add_u64 v[2:3], v[192:193], 0, s[14:15]
	s_mov_b32 s61, m0
	s_mov_b32 m0, s31
	s_nop 0
	global_load_lds_dwordx4 v[2:3], off
	s_mov_b32 m0, s61
	s_waitcnt lgkmcnt(0)
	v_mfma_f32_32x32x16_bf16 v[48:63], v[6:9], v[164:167], v[48:63]
	v_lshl_add_u64 v[2:3], v[14:15], 0, s[22:23]
	s_mov_b32 s61, m0
	s_mov_b32 m0, s60
	s_nop 0
	global_load_lds_dwordx4 v[2:3], off
	s_mov_b32 m0, s61
	ds_read_b128 v[112:115], v208 offset:8192
	ds_read_b128 v[188:191], v208 offset:10240
	ds_read_b128 v[184:187], v209 offset:8192
	ds_read_b128 v[180:183], v209 offset:10240
	ds_read_b128 v[156:159], v208 offset:12288
	ds_read_b128 v[152:155], v208 offset:14336
	ds_read_b128 v[148:151], v209 offset:12288
	ds_read_b128 v[144:147], v209 offset:14336
	s_add_u32 s60, s93, s30
	s_addc_u32 s61, 0, 0
	v_lshl_add_u64 v[2:3], s[60:61], 0, v[10:11]
	v_lshl_add_u64 v[2:3], v[2:3], 0, v[0:1]
	v_lshl_add_u64 v[196:197], s[56:57], 0, v[2:3]
	v_and_b32_e32 v2, 3, v116
	s_add_u32 s6, s6, s60
	v_exp_f32_e32 v96, v64
	v_exp_f32_e32 v97, v65
	v_exp_f32_e32 v98, v66
	v_exp_f32_e32 v99, v67
	v_exp_f32_e32 v100, v68
	v_exp_f32_e32 v101, v69
	v_exp_f32_e32 v102, v70
	v_exp_f32_e32 v103, v71
	v_exp_f32_e32 v104, v72
	v_exp_f32_e32 v105, v73
	v_exp_f32_e32 v106, v74
	v_exp_f32_e32 v107, v75
	v_exp_f32_e32 v108, v76
	v_exp_f32_e32 v109, v77
	v_exp_f32_e32 v110, v78
	v_exp_f32_e32 v111, v79
	v_exp_f32_e32 v80, v48
	v_exp_f32_e32 v81, v49
	v_exp_f32_e32 v82, v50
	v_exp_f32_e32 v83, v51
	v_exp_f32_e32 v84, v52
	v_exp_f32_e32 v85, v53
	v_exp_f32_e32 v86, v54
	v_exp_f32_e32 v87, v55
	v_exp_f32_e32 v88, v56
	v_exp_f32_e32 v89, v57
	v_exp_f32_e32 v90, v58
	v_exp_f32_e32 v91, v59
	v_exp_f32_e32 v92, v60
	v_exp_f32_e32 v93, v61
	v_exp_f32_e32 v94, v62
	v_exp_f32_e32 v95, v63
	v_lshlrev_b32_e32 v2, 4, v2
	v_mov_b32_e32 v3, v1
	s_addc_u32 s7, s7, s61
	s_waitcnt vmcnt(3) lgkmcnt(0)
	s_barrier
	v_lshl_add_u64 v[2:3], s[6:7], 0, v[2:3]
	v_add_u32_e32 v4, 0, v204
	v_lshl_add_u64 v[2:3], v[2:3], 0, v[0:1]
	v_mov_b32_e32 v0, 0
	v_add3_u32 v206, v4, v202, v205
	v_lshl_add_u64 v[198:199], s[58:59], 0, v[2:3]
	v_mov_b32_e32 v48, 0
	v_mov_b32_e32 v49, v0
	v_mov_b32_e32 v50, v0
	v_mov_b32_e32 v51, v0
	v_mov_b32_e32 v52, v0
	v_mov_b32_e32 v53, v0
	v_mov_b32_e32 v54, v0
	v_mov_b32_e32 v55, v0
	v_mov_b32_e32 v56, v0
	v_mov_b32_e32 v57, v0
	v_mov_b32_e32 v58, v0
	v_mov_b32_e32 v59, v0
	v_mov_b32_e32 v60, v0
	v_mov_b32_e32 v61, v0
	v_mov_b32_e32 v62, v0
	v_mov_b32_e32 v63, v0
	v_mov_b32_e32 v64, 0
	v_mov_b32_e32 v65, v0
	v_mov_b32_e32 v66, v0
	v_mov_b32_e32 v67, v0
	v_mov_b32_e32 v68, v0
	v_mov_b32_e32 v69, v0
	v_mov_b32_e32 v70, v0
	v_mov_b32_e32 v71, v0
	v_mov_b32_e32 v72, v0
	v_mov_b32_e32 v73, v0
	v_mov_b32_e32 v74, v0
	v_mov_b32_e32 v75, v0
	v_mov_b32_e32 v76, v0
	v_mov_b32_e32 v77, v0
	v_mov_b32_e32 v78, v0
	v_mov_b32_e32 v79, v0
.LBB0_1313:
	s_mov_b32 s6, s47
	s_mov_b32 s7, s46
	v_add_u32_e32 v214, s7, v206
	ds_read_b64_tr_b16 v[210:211], v214 offset:32768
	ds_read_b64_tr_b16 v[212:213], v214 offset:33280
	v_add_f32_e32 v250, v96, v97
	v_add_f32_e32 v251, v98, v99
	v_add_f32_e32 v252, v100, v101
	v_add_f32_e32 v253, v102, v103
	v_add_f32_e32 v250, v104, v250
	v_cvt_pk_bf16_f32 v160, v96, v97
	v_cvt_pk_bf16_f32 v161, v98, v99
	s_waitcnt lgkmcnt(9)
	v_mfma_f32_32x32x16_bf16 v[128:143], v[112:115], v[172:175], v[32:47]
	ds_read_b64_tr_b16 v[96:97], v214 offset:36864
	ds_read_b64_tr_b16 v[98:99], v214 offset:37376
	s_waitcnt lgkmcnt(10)
	v_mfma_f32_32x32x16_bf16 v[112:127], v[188:191], v[172:175], v[32:47]
	v_add_f32_e32 v251, v105, v251
	v_add_f32_e32 v252, v106, v252
	v_add_f32_e32 v253, v107, v253
	v_add_f32_e32 v250, v108, v250
	v_cvt_pk_bf16_f32 v162, v100, v101
	v_cvt_pk_bf16_f32 v163, v102, v103
	ds_read_b64_tr_b16 v[100:101], v214 offset:33792
	ds_read_b64_tr_b16 v[102:103], v214 offset:34304
	v_add_f32_e32 v251, v109, v251
	v_add_f32_e32 v252, v110, v252
	v_add_f32_e32 v253, v111, v253
	v_add_f32_e32 v250, v80, v250
	v_cvt_pk_bf16_f32 v10, v104, v105
	v_cvt_pk_bf16_f32 v11, v106, v107
	s_waitcnt lgkmcnt(11)
	v_mfma_f32_32x32x16_bf16 v[128:143], v[184:187], v[176:179], v[128:143]
	ds_read_b64_tr_b16 v[104:105], v214 offset:37888
	ds_read_b64_tr_b16 v[106:107], v214 offset:38400
	s_waitcnt lgkmcnt(12)
	v_mfma_f32_32x32x16_bf16 v[112:127], v[180:183], v[176:179], v[112:127]
	v_add_f32_e32 v251, v81, v251
	v_add_f32_e32 v252, v82, v252
	v_add_f32_e32 v253, v83, v253
	v_add_f32_e32 v250, v84, v250
	v_cvt_pk_bf16_f32 v12, v108, v109
	v_cvt_pk_bf16_f32 v13, v110, v111
	ds_read_b64_tr_b16 v[108:109], v214 offset:34816
	ds_read_b64_tr_b16 v[110:111], v214 offset:35328
	v_add_f32_e32 v251, v85, v251
	v_add_f32_e32 v252, v86, v252
	v_add_f32_e32 v253, v87, v253
	v_add_f32_e32 v250, v88, v250
	v_cvt_pk_bf16_f32 v6, v80, v81
	v_cvt_pk_bf16_f32 v7, v82, v83
	s_waitcnt lgkmcnt(13)
	v_mfma_f32_32x32x16_bf16 v[128:143], v[156:159], v[168:171], v[128:143]
	ds_read_b64_tr_b16 v[80:81], v214 offset:38912
	ds_read_b64_tr_b16 v[82:83], v214 offset:39424
	s_waitcnt lgkmcnt(14)
	v_mfma_f32_32x32x16_bf16 v[112:127], v[152:155], v[168:171], v[112:127]
	v_add_f32_e32 v251, v89, v251
	v_add_f32_e32 v252, v90, v252
	v_add_f32_e32 v253, v91, v253
	v_add_f32_e32 v250, v92, v250
	v_cvt_pk_bf16_f32 v8, v84, v85
	v_cvt_pk_bf16_f32 v9, v86, v87
	ds_read_b64_tr_b16 v[84:85], v214 offset:35840
	ds_read_b64_tr_b16 v[86:87], v214 offset:36352
	v_add_f32_e32 v251, v93, v251
	v_add_f32_e32 v252, v94, v252
	v_add_f32_e32 v253, v95, v253
	s_waitcnt lgkmcnt(14)
	v_mfma_f32_32x32x16_bf16 v[128:143], v[148:151], v[164:167], v[128:143]
	v_add_f32_e32 v250, v251, v250
	v_cvt_pk_bf16_f32 v2, v88, v89
	v_cvt_pk_bf16_f32 v3, v90, v91
	ds_read_b64_tr_b16 v[88:89], v214 offset:39936
	ds_read_b64_tr_b16 v[90:91], v214 offset:40448
	v_mfma_f32_32x32x16_bf16 v[112:127], v[144:147], v[164:167], v[112:127]
	v_add_f32_e32 v252, v253, v252
	v_add_f32_e32 v144, v252, v250
	v_cvt_pk_bf16_f32 v4, v92, v93
	v_cvt_pk_bf16_f32 v5, v94, v95
	v_lshl_add_u64 v[92:93], v[196:197], 0, s[14:15]
	s_add_i32 s46, s47, s31
	s_mov_b32 s47, m0
	s_mov_b32 m0, s46
	s_nop 0
	global_load_lds_dwordx4 v[92:93], off
	s_mov_b32 m0, s47
	s_add_i32 s46, s45, s42
	s_mov_b32 s47, m0
	s_mov_b32 m0, s46
	s_nop 0
	global_load_lds_dwordx4 v[194:195], off
	s_mov_b32 m0, s47
	v_add_f32_e32 v0, v0, v144
	s_waitcnt lgkmcnt(14)
	v_mfma_f32_32x32x16_bf16 v[48:63], v[160:163], v[210:213], v[48:63]
	v_exp_f32_e32 v128, v128
	v_exp_f32_e32 v129, v129
	v_exp_f32_e32 v130, v130
	v_exp_f32_e32 v131, v131
	s_waitcnt lgkmcnt(12)
	v_mfma_f32_32x32x16_bf16 v[64:79], v[160:163], v[96:99], v[64:79]
	v_exp_f32_e32 v132, v132
	v_exp_f32_e32 v133, v133
	v_exp_f32_e32 v134, v134
	v_exp_f32_e32 v135, v135
	v_add_u32_e32 v96, s44, v208
	ds_read_b128 v[92:95], v96
	ds_read_b128 v[148:151], v96 offset:2048
	v_add_u32_e32 v97, s44, v209
	s_waitcnt lgkmcnt(12)
	v_mfma_f32_32x32x16_bf16 v[48:63], v[10:13], v[100:103], v[48:63]
	v_exp_f32_e32 v136, v136
	v_exp_f32_e32 v137, v137
	v_exp_f32_e32 v138, v138
	v_exp_f32_e32 v139, v139
	ds_read_b128 v[152:155], v97
	ds_read_b128 v[156:159], v97 offset:2048
	s_waitcnt lgkmcnt(12)
	v_mfma_f32_32x32x16_bf16 v[64:79], v[10:13], v[104:107], v[64:79]
	v_exp_f32_e32 v140, v140
	v_exp_f32_e32 v141, v141
	v_exp_f32_e32 v142, v142
	v_exp_f32_e32 v143, v143
	ds_read_b128 v[180:183], v96 offset:4096
	ds_read_b128 v[184:187], v96 offset:6144
	s_waitcnt lgkmcnt(12)
	v_mfma_f32_32x32x16_bf16 v[48:63], v[6:9], v[108:111], v[48:63]
	v_exp_f32_e32 v112, v112
	v_exp_f32_e32 v113, v113
	v_exp_f32_e32 v114, v114
	v_exp_f32_e32 v115, v115
	ds_read_b128 v[188:191], v97 offset:4096
	ds_read_b128 v[144:147], v97 offset:6144
	s_waitcnt lgkmcnt(12)
	v_mfma_f32_32x32x16_bf16 v[64:79], v[6:9], v[80:83], v[64:79]
	v_exp_f32_e32 v116, v116
	v_exp_f32_e32 v117, v117
	v_exp_f32_e32 v118, v118
	v_exp_f32_e32 v119, v119
	s_waitcnt lgkmcnt(10)
	v_mfma_f32_32x32x16_bf16 v[48:63], v[2:5], v[84:87], v[48:63]
	v_exp_f32_e32 v120, v120
	v_exp_f32_e32 v121, v121
	v_exp_f32_e32 v122, v122
	v_exp_f32_e32 v123, v123
	s_waitcnt lgkmcnt(8)
	v_mfma_f32_32x32x16_bf16 v[64:79], v[2:5], v[88:91], v[64:79]
	v_exp_f32_e32 v124, v124
	v_exp_f32_e32 v125, v125
	v_exp_f32_e32 v126, v126
	v_exp_f32_e32 v127, v127
	s_waitcnt vmcnt(4) lgkmcnt(0)
	s_barrier
	v_add_u32_e32 v218, s6, v206
	ds_read_b64_tr_b16 v[210:211], v218 offset:32768
	ds_read_b64_tr_b16 v[212:213], v218 offset:33280
	s_waitcnt lgkmcnt(9)
	v_mfma_f32_32x32x16_bf16 v[96:111], v[92:95], v[172:175], v[32:47]
	v_add_f32_e32 v250, v128, v129
	v_add_f32_e32 v251, v130, v131
	v_add_f32_e32 v252, v132, v133
	v_add_f32_e32 v253, v134, v135
	v_add_f32_e32 v250, v136, v250
	v_cvt_pk_bf16_f32 v160, v128, v129
	v_cvt_pk_bf16_f32 v161, v130, v131
	ds_read_b64_tr_b16 v[128:129], v218 offset:36864
	ds_read_b64_tr_b16 v[130:131], v218 offset:37376
	s_waitcnt lgkmcnt(10)
	v_mfma_f32_32x32x16_bf16 v[80:95], v[148:151], v[172:175], v[32:47]
	v_add_f32_e32 v251, v137, v251
	v_add_f32_e32 v252, v138, v252
	v_add_f32_e32 v253, v139, v253
	v_add_f32_e32 v250, v140, v250
	v_cvt_pk_bf16_f32 v162, v132, v133
	v_cvt_pk_bf16_f32 v163, v134, v135
	ds_read_b64_tr_b16 v[132:133], v218 offset:33792
	ds_read_b64_tr_b16 v[134:135], v218 offset:34304
	s_waitcnt lgkmcnt(11)
	v_mfma_f32_32x32x16_bf16 v[96:111], v[152:155], v[176:179], v[96:111]
	v_add_f32_e32 v251, v141, v251
	v_add_f32_e32 v252, v142, v252
	v_add_f32_e32 v253, v143, v253
	v_add_f32_e32 v250, v112, v250
	v_cvt_pk_bf16_f32 v10, v136, v137
	v_cvt_pk_bf16_f32 v11, v138, v139
	ds_read_b64_tr_b16 v[136:137], v218 offset:37888
	ds_read_b64_tr_b16 v[138:139], v218 offset:38400
	s_waitcnt lgkmcnt(12)
	v_mfma_f32_32x32x16_bf16 v[80:95], v[156:159], v[176:179], v[80:95]
	v_add_f32_e32 v251, v113, v251
	v_add_f32_e32 v252, v114, v252
	v_add_f32_e32 v253, v115, v253
	v_add_f32_e32 v250, v116, v250
	v_cvt_pk_bf16_f32 v12, v140, v141
	v_cvt_pk_bf16_f32 v13, v142, v143
	ds_read_b64_tr_b16 v[140:141], v218 offset:34816
	ds_read_b64_tr_b16 v[142:143], v218 offset:35328
	s_waitcnt lgkmcnt(13)
	v_mfma_f32_32x32x16_bf16 v[96:111], v[180:183], v[168:171], v[96:111]
	v_add_f32_e32 v251, v117, v251
	v_add_f32_e32 v252, v118, v252
	v_add_f32_e32 v253, v119, v253
	v_add_f32_e32 v250, v120, v250
	v_cvt_pk_bf16_f32 v6, v112, v113
	v_cvt_pk_bf16_f32 v7, v114, v115
	ds_read_b64_tr_b16 v[214:215], v218 offset:38912
	ds_read_b64_tr_b16 v[216:217], v218 offset:39424
	s_waitcnt lgkmcnt(14)
	v_mfma_f32_32x32x16_bf16 v[80:95], v[184:187], v[168:171], v[80:95]
	v_add_f32_e32 v251, v121, v251
	v_add_f32_e32 v252, v122, v252
	v_add_f32_e32 v253, v123, v253
	v_add_f32_e32 v250, v124, v250
	v_cvt_pk_bf16_f32 v8, v116, v117
	v_cvt_pk_bf16_f32 v9, v118, v119
	ds_read_b64_tr_b16 v[116:117], v218 offset:35840
	ds_read_b64_tr_b16 v[118:119], v218 offset:36352
	s_waitcnt lgkmcnt(14)
	v_mfma_f32_32x32x16_bf16 v[96:111], v[188:191], v[164:167], v[96:111]
	v_add_f32_e32 v251, v125, v251
	v_add_f32_e32 v252, v126, v252
	v_add_f32_e32 v253, v127, v253
	v_add_f32_e32 v250, v251, v250
	v_cvt_pk_bf16_f32 v2, v120, v121
	v_cvt_pk_bf16_f32 v3, v122, v123
	ds_read_b64_tr_b16 v[120:121], v218 offset:39936
	ds_read_b64_tr_b16 v[122:123], v218 offset:40448
	v_mfma_f32_32x32x16_bf16 v[80:95], v[144:147], v[164:167], v[80:95]
	v_add_f32_e32 v252, v253, v252
	v_add_f32_e32 v112, v252, v250
	v_cvt_pk_bf16_f32 v4, v124, v125
	v_cvt_pk_bf16_f32 v5, v126, v127
	s_nop 0
	v_add_f32_e32 v0, v0, v112
	v_lshl_add_u64 v[112:113], v[196:197], 0, s[40:41]
	s_add_i32 s46, s44, s31
	s_mov_b32 s47, m0
	s_mov_b32 m0, s46
	s_nop 0
	global_load_lds_dwordx4 v[112:113], off
	s_mov_b32 m0, s47
	v_lshl_add_u64 v[112:113], v[198:199], 0, s[24:25]
	s_add_i32 s46, s7, s42
	s_mov_b32 s47, m0
	s_mov_b32 m0, s46
	s_nop 0
	global_load_lds_dwordx4 v[112:113], off
	s_mov_b32 m0, s47
	s_waitcnt lgkmcnt(14)
	v_mfma_f32_32x32x16_bf16 v[48:63], v[160:163], v[210:213], v[48:63]
	v_exp_f32_e32 v96, v96
	v_exp_f32_e32 v97, v97
	v_exp_f32_e32 v98, v98
	v_exp_f32_e32 v99, v99
	s_waitcnt lgkmcnt(12)
	v_mfma_f32_32x32x16_bf16 v[64:79], v[160:163], v[128:131], v[64:79]
	v_exp_f32_e32 v100, v100
	v_exp_f32_e32 v101, v101
	v_exp_f32_e32 v102, v102
	v_exp_f32_e32 v103, v103
	v_add_u32_e32 v124, s45, v208
	ds_read_b128 v[112:115], v124
	ds_read_b128 v[188:191], v124 offset:2048
	v_add_u32_e32 v125, s45, v209
	s_waitcnt lgkmcnt(12)
	v_mfma_f32_32x32x16_bf16 v[48:63], v[10:13], v[132:135], v[48:63]
	v_exp_f32_e32 v104, v104
	v_exp_f32_e32 v105, v105
	v_exp_f32_e32 v106, v106
	v_exp_f32_e32 v107, v107
	ds_read_b128 v[184:187], v125
	ds_read_b128 v[180:183], v125 offset:2048
	s_waitcnt lgkmcnt(12)
	v_mfma_f32_32x32x16_bf16 v[64:79], v[10:13], v[136:139], v[64:79]
	v_exp_f32_e32 v108, v108
	v_exp_f32_e32 v109, v109
	v_exp_f32_e32 v110, v110
	v_exp_f32_e32 v111, v111
	ds_read_b128 v[156:159], v124 offset:4096
	ds_read_b128 v[152:155], v124 offset:6144
	s_waitcnt lgkmcnt(12)
	v_mfma_f32_32x32x16_bf16 v[48:63], v[6:9], v[140:143], v[48:63]
	v_exp_f32_e32 v80, v80
	v_exp_f32_e32 v81, v81
	v_exp_f32_e32 v82, v82
	v_exp_f32_e32 v83, v83
	ds_read_b128 v[148:151], v125 offset:4096
	ds_read_b128 v[144:147], v125 offset:6144
	s_waitcnt lgkmcnt(12)
	v_mfma_f32_32x32x16_bf16 v[64:79], v[6:9], v[214:217], v[64:79]
	v_exp_f32_e32 v84, v84
	v_exp_f32_e32 v85, v85
	v_exp_f32_e32 v86, v86
	v_exp_f32_e32 v87, v87
	s_waitcnt lgkmcnt(10)
	v_mfma_f32_32x32x16_bf16 v[48:63], v[2:5], v[116:119], v[48:63]
	v_exp_f32_e32 v88, v88
	v_exp_f32_e32 v89, v89
	v_exp_f32_e32 v90, v90
	v_exp_f32_e32 v91, v91
	s_waitcnt lgkmcnt(8)
	v_mfma_f32_32x32x16_bf16 v[64:79], v[2:5], v[120:123], v[64:79]
	v_exp_f32_e32 v92, v92
	v_exp_f32_e32 v93, v93
	v_exp_f32_e32 v94, v94
	v_exp_f32_e32 v95, v95
	s_waitcnt vmcnt(4) lgkmcnt(0)
	s_barrier
	s_add_i32 s43, s43, 2
	v_lshl_add_u64 v[194:195], v[194:195], 0, s[22:23]
	v_lshl_add_u64 v[196:197], v[196:197], 0, s[22:23]
	v_lshl_add_u64 v[198:199], v[198:199], 0, s[22:23]
	s_mov_b32 s46, s44
	s_mov_b32 s47, s45
	s_mov_b32 s44, s7
	s_cmp_gt_u32 s43, 60
	s_mov_b32 s45, s6
	s_cbranch_scc0 .LBB0_1313
	s_and_b32 s6, s21, 0x3fffffc0
	s_lshl_b32 s6, s6, 2
	s_add_i32 s31, s6, 0
	s_add_i32 s31, s31, 0x10000
	ds_read_b64_tr_b16 v[194:195], v206 offset:49152
	ds_read_b64_tr_b16 v[196:197], v206 offset:49664
	s_waitcnt lgkmcnt(9)
	v_mfma_f32_32x32x16_bf16 v[128:143], v[112:115], v[172:175], v[32:47]
	v_add_f32_e32 v250, v96, v97
	v_add_f32_e32 v251, v98, v99
	v_add_f32_e32 v252, v100, v101
	v_add_f32_e32 v253, v102, v103
	v_add_f32_e32 v250, v104, v250
	v_cvt_pk_bf16_f32 v160, v96, v97
	v_cvt_pk_bf16_f32 v161, v98, v99
	ds_read_b64_tr_b16 v[96:97], v206 offset:53248
	ds_read_b64_tr_b16 v[98:99], v206 offset:53760
	v_add_f32_e32 v251, v105, v251
	v_add_f32_e32 v252, v106, v252
	v_add_f32_e32 v253, v107, v253
	v_add_f32_e32 v250, v108, v250
	v_cvt_pk_bf16_f32 v162, v100, v101
	v_cvt_pk_bf16_f32 v163, v102, v103
	s_waitcnt lgkmcnt(10)
	v_mfma_f32_32x32x16_bf16 v[112:127], v[188:191], v[172:175], v[32:47]
	ds_read_b64_tr_b16 v[100:101], v206 offset:50176
	ds_read_b64_tr_b16 v[102:103], v206 offset:50688
	s_waitcnt lgkmcnt(11)
	v_mfma_f32_32x32x16_bf16 v[128:143], v[184:187], v[176:179], v[128:143]
	v_add_f32_e32 v251, v109, v251
	v_add_f32_e32 v252, v110, v252
	v_add_f32_e32 v253, v111, v253
	v_add_f32_e32 v250, v80, v250
	v_cvt_pk_bf16_f32 v10, v104, v105
	v_cvt_pk_bf16_f32 v11, v106, v107
	ds_read_b64_tr_b16 v[104:105], v206 offset:54272
	ds_read_b64_tr_b16 v[106:107], v206 offset:54784
	v_add_f32_e32 v251, v81, v251
	v_add_f32_e32 v252, v82, v252
	v_add_f32_e32 v253, v83, v253
	v_add_f32_e32 v250, v84, v250
	v_cvt_pk_bf16_f32 v12, v108, v109
	v_cvt_pk_bf16_f32 v13, v110, v111
	s_waitcnt lgkmcnt(12)
	v_mfma_f32_32x32x16_bf16 v[112:127], v[180:183], v[176:179], v[112:127]
	ds_read_b64_tr_b16 v[108:109], v206 offset:51200
	ds_read_b64_tr_b16 v[110:111], v206 offset:51712
	s_waitcnt lgkmcnt(13)
	v_mfma_f32_32x32x16_bf16 v[128:143], v[156:159], v[168:171], v[128:143]
	v_add_f32_e32 v251, v85, v251
	v_add_f32_e32 v252, v86, v252
	v_add_f32_e32 v253, v87, v253
	v_add_f32_e32 v250, v88, v250
	v_cvt_pk_bf16_f32 v6, v80, v81
	v_cvt_pk_bf16_f32 v7, v82, v83
	ds_read_b64_tr_b16 v[80:81], v206 offset:55296
	ds_read_b64_tr_b16 v[82:83], v206 offset:55808
	v_add_f32_e32 v251, v89, v251
	v_add_f32_e32 v252, v90, v252
	v_add_f32_e32 v253, v91, v253
	v_add_f32_e32 v250, v92, v250
	v_cvt_pk_bf16_f32 v8, v84, v85
	v_cvt_pk_bf16_f32 v9, v86, v87
	s_waitcnt lgkmcnt(14)
	v_mfma_f32_32x32x16_bf16 v[112:127], v[152:155], v[168:171], v[112:127]
	ds_read_b64_tr_b16 v[84:85], v206 offset:52224
	ds_read_b64_tr_b16 v[86:87], v206 offset:52736
	s_waitcnt lgkmcnt(14)
	v_mfma_f32_32x32x16_bf16 v[128:143], v[148:151], v[164:167], v[128:143]
	v_add_f32_e32 v251, v93, v251
	v_add_f32_e32 v252, v94, v252
	v_add_f32_e32 v253, v95, v253
	v_add_f32_e32 v250, v251, v250
	v_cvt_pk_bf16_f32 v2, v88, v89
	v_cvt_pk_bf16_f32 v3, v90, v91
	ds_read_b64_tr_b16 v[88:89], v206 offset:56320
	ds_read_b64_tr_b16 v[90:91], v206 offset:56832
	v_add_f32_e32 v252, v253, v252
	v_add_f32_e32 v148, v252, v250
	v_cvt_pk_bf16_f32 v4, v92, v93
	v_cvt_pk_bf16_f32 v5, v94, v95
	v_mfma_f32_32x32x16_bf16 v[112:127], v[144:147], v[164:167], v[112:127]
	s_mov_b64 s[42:43], 0x10c000
	v_lshl_add_u64 v[92:93], v[192:193], 0, s[42:43]
	s_mov_b32 s6, m0
	s_mov_b32 m0, s20
	s_nop 0
	global_load_lds_dwordx4 v[92:93], off
	s_mov_b32 m0, s6
	s_mov_b64 s[6:7], 0x104000
	s_cmp_lg_u32 0, -1
	v_lshl_add_u64 v[92:93], v[14:15], 0, s[6:7]
	s_cselect_b32 s6, 0, 0
	s_add_i32 s7, s6, s8
	s_add_i32 s20, s7, 0xa000
	s_mov_b32 s21, m0
	s_mov_b32 m0, s20
	s_nop 0
	global_load_lds_dwordx4 v[92:93], off
	s_mov_b32 m0, s21
	v_add_f32_e32 v0, v0, v148
	s_waitcnt lgkmcnt(14)
	v_mfma_f32_32x32x16_bf16 v[48:63], v[160:163], v[194:197], v[48:63]
	v_exp_f32_e32 v128, v128
	v_exp_f32_e32 v129, v129
	v_exp_f32_e32 v130, v130
	v_exp_f32_e32 v131, v131
	s_waitcnt lgkmcnt(12)
	v_mfma_f32_32x32x16_bf16 v[64:79], v[160:163], v[96:99], v[64:79]
	v_exp_f32_e32 v132, v132
	v_exp_f32_e32 v133, v133
	v_exp_f32_e32 v134, v134
	v_exp_f32_e32 v135, v135
	ds_read_b128 v[92:95], v208
	ds_read_b128 v[180:183], v208 offset:2048
	s_waitcnt lgkmcnt(12)
	v_mfma_f32_32x32x16_bf16 v[48:63], v[10:13], v[100:103], v[48:63]
	v_exp_f32_e32 v136, v136
	v_exp_f32_e32 v137, v137
	v_exp_f32_e32 v138, v138
	v_exp_f32_e32 v139, v139
	ds_read_b128 v[100:103], v209
	ds_read_b128 v[184:187], v209 offset:2048
	s_waitcnt lgkmcnt(12)
	v_mfma_f32_32x32x16_bf16 v[64:79], v[10:13], v[104:107], v[64:79]
	v_exp_f32_e32 v140, v140
	v_exp_f32_e32 v141, v141
	v_exp_f32_e32 v142, v142
	v_exp_f32_e32 v143, v143
	ds_read_b128 v[104:107], v208 offset:4096
	ds_read_b128 v[188:191], v208 offset:6144
	s_waitcnt lgkmcnt(12)
	v_mfma_f32_32x32x16_bf16 v[48:63], v[6:9], v[108:111], v[48:63]
	v_exp_f32_e32 v112, v112
	v_exp_f32_e32 v113, v113
	v_exp_f32_e32 v114, v114
	v_exp_f32_e32 v115, v115
	ds_read_b128 v[108:111], v209 offset:4096
	ds_read_b128 v[96:99], v209 offset:6144
	s_waitcnt lgkmcnt(12)
	v_mfma_f32_32x32x16_bf16 v[64:79], v[6:9], v[80:83], v[64:79]
	v_exp_f32_e32 v116, v116
	v_exp_f32_e32 v117, v117
	v_exp_f32_e32 v118, v118
	v_exp_f32_e32 v119, v119
	s_waitcnt lgkmcnt(10)
	v_mfma_f32_32x32x16_bf16 v[48:63], v[2:5], v[84:87], v[48:63]
	v_exp_f32_e32 v120, v120
	v_exp_f32_e32 v121, v121
	v_exp_f32_e32 v122, v122
	v_exp_f32_e32 v123, v123
	s_waitcnt lgkmcnt(8)
	v_mfma_f32_32x32x16_bf16 v[64:79], v[2:5], v[88:91], v[64:79]
	v_exp_f32_e32 v124, v124
	v_exp_f32_e32 v125, v125
	v_exp_f32_e32 v126, v126
	v_exp_f32_e32 v127, v127
	s_waitcnt vmcnt(4) lgkmcnt(0)
	s_barrier
	ds_read_b64_tr_b16 v[192:193], v206 offset:57344
	ds_read_b64_tr_b16 v[194:195], v206 offset:57856
	v_add_f32_e32 v250, v128, v129
	v_add_f32_e32 v251, v130, v131
	v_add_f32_e32 v252, v132, v133
	v_add_f32_e32 v253, v134, v135
	v_add_f32_e32 v250, v136, v250
	v_cvt_pk_bf16_f32 v160, v128, v129
	v_cvt_pk_bf16_f32 v161, v130, v131
	s_waitcnt lgkmcnt(9)
	v_mfma_f32_32x32x16_bf16 v[144:159], v[92:95], v[172:175], v[32:47]
	ds_read_b64_tr_b16 v[128:129], v206 offset:61440
	ds_read_b64_tr_b16 v[130:131], v206 offset:61952
	s_waitcnt lgkmcnt(10)
	v_mfma_f32_32x32x16_bf16 v[80:95], v[180:183], v[172:175], v[32:47]
	v_add_f32_e32 v251, v137, v251
	v_add_f32_e32 v252, v138, v252
	v_add_f32_e32 v253, v139, v253
	v_add_f32_e32 v250, v140, v250
	v_cvt_pk_bf16_f32 v162, v132, v133
	v_cvt_pk_bf16_f32 v163, v134, v135
	ds_read_b64_tr_b16 v[132:133], v206 offset:58368
	ds_read_b64_tr_b16 v[134:135], v206 offset:58880
	v_add_f32_e32 v251, v141, v251
	v_add_f32_e32 v252, v142, v252
	v_add_f32_e32 v253, v143, v253
	v_add_f32_e32 v250, v112, v250
	v_cvt_pk_bf16_f32 v10, v136, v137
	v_cvt_pk_bf16_f32 v11, v138, v139
	s_waitcnt lgkmcnt(11)
	v_mfma_f32_32x32x16_bf16 v[144:159], v[100:103], v[176:179], v[144:159]
	ds_read_b64_tr_b16 v[100:101], v206 offset:62464
	ds_read_b64_tr_b16 v[102:103], v206 offset:62976
	s_waitcnt lgkmcnt(12)
	v_mfma_f32_32x32x16_bf16 v[80:95], v[184:187], v[176:179], v[80:95]
	v_add_f32_e32 v251, v113, v251
	v_add_f32_e32 v252, v114, v252
	v_add_f32_e32 v253, v115, v253
	v_add_f32_e32 v250, v116, v250
	v_cvt_pk_bf16_f32 v12, v140, v141
	v_cvt_pk_bf16_f32 v13, v142, v143
	ds_read_b64_tr_b16 v[136:137], v206 offset:59392
	ds_read_b64_tr_b16 v[138:139], v206 offset:59904
	v_add_f32_e32 v251, v117, v251
	v_add_f32_e32 v252, v118, v252
	v_add_f32_e32 v253, v119, v253
	v_add_f32_e32 v250, v120, v250
	v_cvt_pk_bf16_f32 v6, v112, v113
	v_cvt_pk_bf16_f32 v7, v114, v115
	s_waitcnt lgkmcnt(13)
	v_mfma_f32_32x32x16_bf16 v[144:159], v[104:107], v[168:171], v[144:159]
	ds_read_b64_tr_b16 v[104:105], v206 offset:63488
	ds_read_b64_tr_b16 v[106:107], v206 offset:64000
	s_waitcnt lgkmcnt(14)
	v_mfma_f32_32x32x16_bf16 v[80:95], v[188:191], v[168:171], v[80:95]
	v_add_f32_e32 v251, v121, v251
	v_add_f32_e32 v252, v122, v252
	v_add_f32_e32 v253, v123, v253
	v_add_f32_e32 v250, v124, v250
	v_cvt_pk_bf16_f32 v8, v116, v117
	v_cvt_pk_bf16_f32 v9, v118, v119
	ds_read_b64_tr_b16 v[116:117], v206 offset:60416
	ds_read_b64_tr_b16 v[118:119], v206 offset:60928
	v_add_f32_e32 v251, v125, v251
	v_add_f32_e32 v252, v126, v252
	v_add_f32_e32 v253, v127, v253
	v_add_f32_e32 v250, v251, v250
	v_cvt_pk_bf16_f32 v2, v120, v121
	v_cvt_pk_bf16_f32 v3, v122, v123
	s_waitcnt lgkmcnt(14)
	v_mfma_f32_32x32x16_bf16 v[144:159], v[108:111], v[164:167], v[144:159]
	ds_read_b64_tr_b16 v[108:109], v206 offset:64512
	ds_read_b64_tr_b16 v[110:111], v206 offset:65024
	v_mfma_f32_32x32x16_bf16 v[80:95], v[96:99], v[164:167], v[80:95]
	v_add_f32_e32 v252, v253, v252
	v_add_f32_e32 v96, v252, v250
	v_cvt_pk_bf16_f32 v4, v124, v125
	v_cvt_pk_bf16_f32 v5, v126, v127
	s_mov_b64 s[20:21], 0x108000
	v_add_f32_e32 v0, v0, v96
	v_lshl_add_u64 v[96:97], v[14:15], 0, s[20:21]
	s_add_i32 s7, s7, 0xc000
	s_mov_b32 s20, m0
	s_mov_b32 m0, s7
	s_nop 0
	global_load_lds_dwordx4 v[96:97], off
	s_mov_b32 m0, s20
	s_waitcnt lgkmcnt(14)
	v_mfma_f32_32x32x16_bf16 v[48:63], v[160:163], v[192:195], v[48:63]
	v_exp_f32_e32 v144, v144
	v_exp_f32_e32 v145, v145
	v_exp_f32_e32 v146, v146
	v_exp_f32_e32 v147, v147
	s_waitcnt lgkmcnt(12)
	v_mfma_f32_32x32x16_bf16 v[64:79], v[160:163], v[128:131], v[64:79]
	v_exp_f32_e32 v148, v148
	v_exp_f32_e32 v149, v149
	v_exp_f32_e32 v150, v150
	v_exp_f32_e32 v151, v151
	ds_read_b128 v[96:99], v208 offset:8192
	ds_read_b128 v[120:123], v208 offset:10240
	s_waitcnt lgkmcnt(12)
	v_mfma_f32_32x32x16_bf16 v[48:63], v[10:13], v[132:135], v[48:63]
	v_exp_f32_e32 v152, v152
	v_exp_f32_e32 v153, v153
	v_exp_f32_e32 v154, v154
	v_exp_f32_e32 v155, v155
	ds_read_b128 v[124:127], v209 offset:8192
	ds_read_b128 v[180:183], v209 offset:10240
	s_waitcnt lgkmcnt(12)
	v_mfma_f32_32x32x16_bf16 v[64:79], v[10:13], v[100:103], v[64:79]
	v_exp_f32_e32 v156, v156
	v_exp_f32_e32 v157, v157
	v_exp_f32_e32 v158, v158
	v_exp_f32_e32 v159, v159
	ds_read_b128 v[184:187], v208 offset:12288
	ds_read_b128 v[188:191], v208 offset:14336
	s_waitcnt lgkmcnt(12)
	v_mfma_f32_32x32x16_bf16 v[48:63], v[6:9], v[136:139], v[48:63]
	v_exp_f32_e32 v80, v80
	v_exp_f32_e32 v81, v81
	v_exp_f32_e32 v82, v82
	v_exp_f32_e32 v83, v83
	ds_read_b128 v[192:195], v209 offset:12288
	ds_read_b128 v[112:115], v209 offset:14336
	s_waitcnt lgkmcnt(12)
	v_mfma_f32_32x32x16_bf16 v[64:79], v[6:9], v[104:107], v[64:79]
	v_exp_f32_e32 v84, v84
	v_exp_f32_e32 v85, v85
	v_exp_f32_e32 v86, v86
	v_exp_f32_e32 v87, v87
	s_waitcnt lgkmcnt(10)
	v_mfma_f32_32x32x16_bf16 v[48:63], v[2:5], v[116:119], v[48:63]
	v_exp_f32_e32 v88, v88
	v_exp_f32_e32 v89, v89
	v_exp_f32_e32 v90, v90
	v_exp_f32_e32 v91, v91
	s_waitcnt lgkmcnt(8)
	v_mfma_f32_32x32x16_bf16 v[64:79], v[2:5], v[108:111], v[64:79]
	v_exp_f32_e32 v92, v92
	v_exp_f32_e32 v93, v93
	v_exp_f32_e32 v94, v94
	v_exp_f32_e32 v95, v95
	s_waitcnt vmcnt(3) lgkmcnt(0)
	s_barrier
	ds_read_b64_tr_b16 v[116:117], v206 offset:32768
	ds_read_b64_tr_b16 v[118:119], v206 offset:33280
	s_waitcnt lgkmcnt(9)
	v_mfma_f32_32x32x16_bf16 v[128:143], v[96:99], v[172:175], v[32:47]
	v_add_f32_e32 v250, v144, v145
	v_add_f32_e32 v251, v146, v147
	v_add_f32_e32 v252, v148, v149
	v_add_f32_e32 v253, v150, v151
	v_add_f32_e32 v250, v152, v250
	v_cvt_pk_bf16_f32 v160, v144, v145
	v_cvt_pk_bf16_f32 v161, v146, v147
	ds_read_b64_tr_b16 v[144:145], v206 offset:36864
	ds_read_b64_tr_b16 v[146:147], v206 offset:37376
	v_add_f32_e32 v251, v153, v251
	v_add_f32_e32 v252, v154, v252
	v_add_f32_e32 v253, v155, v253
	v_add_f32_e32 v250, v156, v250
	v_cvt_pk_bf16_f32 v162, v148, v149
	v_cvt_pk_bf16_f32 v163, v150, v151
	s_waitcnt lgkmcnt(10)
	v_mfma_f32_32x32x16_bf16 v[96:111], v[120:123], v[172:175], v[32:47]
	ds_read_b64_tr_b16 v[120:121], v206 offset:33792
	ds_read_b64_tr_b16 v[122:123], v206 offset:34304
	s_waitcnt lgkmcnt(11)
	v_mfma_f32_32x32x16_bf16 v[128:143], v[124:127], v[176:179], v[128:143]
	v_add_f32_e32 v251, v157, v251
	v_add_f32_e32 v252, v158, v252
	v_add_f32_e32 v253, v159, v253
	v_add_f32_e32 v250, v80, v250
	v_cvt_pk_bf16_f32 v10, v152, v153
	v_cvt_pk_bf16_f32 v11, v154, v155
	ds_read_b64_tr_b16 v[124:125], v206 offset:37888
	ds_read_b64_tr_b16 v[126:127], v206 offset:38400
	v_add_f32_e32 v251, v81, v251
	v_add_f32_e32 v252, v82, v252
	v_add_f32_e32 v253, v83, v253
	v_add_f32_e32 v250, v84, v250
	v_cvt_pk_bf16_f32 v12, v156, v157
	v_cvt_pk_bf16_f32 v13, v158, v159
	s_waitcnt lgkmcnt(12)
	v_mfma_f32_32x32x16_bf16 v[96:111], v[180:183], v[176:179], v[96:111]
	ds_read_b64_tr_b16 v[148:149], v206 offset:34816
	ds_read_b64_tr_b16 v[150:151], v206 offset:35328
	s_waitcnt lgkmcnt(13)
	v_mfma_f32_32x32x16_bf16 v[128:143], v[184:187], v[168:171], v[128:143]
	v_add_f32_e32 v251, v85, v251
	v_add_f32_e32 v252, v86, v252
	v_add_f32_e32 v253, v87, v253
	v_add_f32_e32 v250, v88, v250
	v_cvt_pk_bf16_f32 v6, v80, v81
	v_cvt_pk_bf16_f32 v7, v82, v83
	ds_read_b64_tr_b16 v[80:81], v206 offset:38912
	ds_read_b64_tr_b16 v[82:83], v206 offset:39424
	v_add_f32_e32 v251, v89, v251
	v_add_f32_e32 v252, v90, v252
	v_add_f32_e32 v253, v91, v253
	v_add_f32_e32 v250, v92, v250
	v_cvt_pk_bf16_f32 v8, v84, v85
	v_cvt_pk_bf16_f32 v9, v86, v87
	s_waitcnt lgkmcnt(14)
	v_mfma_f32_32x32x16_bf16 v[96:111], v[188:191], v[168:171], v[96:111]
	ds_read_b64_tr_b16 v[84:85], v206 offset:35840
	ds_read_b64_tr_b16 v[86:87], v206 offset:36352
	s_waitcnt lgkmcnt(14)
	v_mfma_f32_32x32x16_bf16 v[128:143], v[192:195], v[164:167], v[128:143]
	v_add_f32_e32 v251, v93, v251
	v_add_f32_e32 v252, v94, v252
	v_add_f32_e32 v253, v95, v253
	v_add_f32_e32 v250, v251, v250
	v_cvt_pk_bf16_f32 v2, v88, v89
	v_cvt_pk_bf16_f32 v3, v90, v91
	ds_read_b64_tr_b16 v[88:89], v206 offset:39936
	ds_read_b64_tr_b16 v[90:91], v206 offset:40448
	v_add_f32_e32 v252, v253, v252
	v_add_f32_e32 v152, v252, v250
	v_cvt_pk_bf16_f32 v4, v92, v93
	v_cvt_pk_bf16_f32 v5, v94, v95
	v_mfma_f32_32x32x16_bf16 v[96:111], v[112:115], v[164:167], v[96:111]
	s_add_i32 s6, s6, 0xe000
	v_lshl_add_u64 v[14:15], v[14:15], 0, s[42:43]
	s_add_i32 s8, s8, s6
	s_mov_b32 s7, m0
	s_mov_b32 m0, s8
	s_nop 0
	global_load_lds_dwordx4 v[14:15], off
	s_mov_b32 m0, s7
	v_add_f32_e32 v0, v0, v152
	s_mov_b64 s[80:81], 0x10c000
	s_waitcnt lgkmcnt(14)
	v_mfma_f32_32x32x16_bf16 v[48:63], v[160:163], v[116:119], v[48:63]
	v_exp_f32_e32 v128, v128
	v_exp_f32_e32 v129, v129
	v_exp_f32_e32 v130, v130
	v_exp_f32_e32 v131, v131
	s_waitcnt lgkmcnt(12)
	v_mfma_f32_32x32x16_bf16 v[64:79], v[160:163], v[144:147], v[64:79]
	v_exp_f32_e32 v132, v132
	v_exp_f32_e32 v133, v133
	v_exp_f32_e32 v134, v134
	v_exp_f32_e32 v135, v135
	ds_read_b128 v[92:95], v208 offset:16384
	ds_read_b128 v[152:155], v208 offset:18432
	s_waitcnt lgkmcnt(12)
	v_mfma_f32_32x32x16_bf16 v[48:63], v[10:13], v[120:123], v[48:63]
	v_exp_f32_e32 v136, v136
	v_exp_f32_e32 v137, v137
	v_exp_f32_e32 v138, v138
	v_exp_f32_e32 v139, v139
	ds_read_b128 v[156:159], v209 offset:16384
	ds_read_b128 v[180:183], v209 offset:18432
	s_waitcnt lgkmcnt(12)
	v_mfma_f32_32x32x16_bf16 v[64:79], v[10:13], v[124:127], v[64:79]
	v_exp_f32_e32 v140, v140
	v_exp_f32_e32 v141, v141
	v_exp_f32_e32 v142, v142
	v_exp_f32_e32 v143, v143
	ds_read_b128 v[184:187], v208 offset:20480
	ds_read_b128 v[188:191], v208 offset:22528
	s_waitcnt lgkmcnt(12)
	v_mfma_f32_32x32x16_bf16 v[48:63], v[6:9], v[148:151], v[48:63]
	v_exp_f32_e32 v96, v96
	v_exp_f32_e32 v97, v97
	v_exp_f32_e32 v98, v98
	v_exp_f32_e32 v99, v99
	ds_read_b128 v[148:151], v209 offset:20480
	ds_read_b128 v[144:147], v209 offset:22528
	s_waitcnt lgkmcnt(12)
	v_mfma_f32_32x32x16_bf16 v[64:79], v[6:9], v[80:83], v[64:79]
	v_exp_f32_e32 v100, v100
	v_exp_f32_e32 v101, v101
	v_exp_f32_e32 v102, v102
	v_exp_f32_e32 v103, v103
	s_waitcnt lgkmcnt(10)
	v_mfma_f32_32x32x16_bf16 v[48:63], v[2:5], v[84:87], v[48:63]
	v_exp_f32_e32 v104, v104
	v_exp_f32_e32 v105, v105
	v_exp_f32_e32 v106, v106
	v_exp_f32_e32 v107, v107
	s_waitcnt lgkmcnt(8)
	v_mfma_f32_32x32x16_bf16 v[64:79], v[2:5], v[88:91], v[64:79]
	v_exp_f32_e32 v108, v108
	v_exp_f32_e32 v109, v109
	v_exp_f32_e32 v110, v110
	v_exp_f32_e32 v111, v111
	s_waitcnt vmcnt(2) lgkmcnt(0)
	s_barrier
	ds_read_b64_tr_b16 v[192:193], v206 offset:40960
	ds_read_b64_tr_b16 v[194:195], v206 offset:41472
	v_add_f32_e32 v250, v128, v129
	v_add_f32_e32 v251, v130, v131
	v_add_f32_e32 v252, v132, v133
	v_add_f32_e32 v253, v134, v135
	v_add_f32_e32 v250, v136, v250
	v_cvt_pk_bf16_f32 v160, v128, v129
	v_cvt_pk_bf16_f32 v161, v130, v131
	s_waitcnt lgkmcnt(9)
	v_mfma_f32_32x32x16_bf16 v[112:127], v[92:95], v[172:175], v[32:47]
	ds_read_b64_tr_b16 v[128:129], v206 offset:45056
	ds_read_b64_tr_b16 v[130:131], v206 offset:45568
	s_waitcnt lgkmcnt(10)
	v_mfma_f32_32x32x16_bf16 v[80:95], v[152:155], v[172:175], v[32:47]
	v_add_f32_e32 v251, v137, v251
	v_add_f32_e32 v252, v138, v252
	v_add_f32_e32 v253, v139, v253
	v_add_f32_e32 v250, v140, v250
	v_cvt_pk_bf16_f32 v162, v132, v133
	v_cvt_pk_bf16_f32 v163, v134, v135
	ds_read_b64_tr_b16 v[132:133], v206 offset:41984
	ds_read_b64_tr_b16 v[134:135], v206 offset:42496
	v_add_f32_e32 v251, v141, v251
	v_add_f32_e32 v252, v142, v252
	v_add_f32_e32 v253, v143, v253
	v_add_f32_e32 v250, v96, v250
	v_cvt_pk_bf16_f32 v10, v136, v137
	v_cvt_pk_bf16_f32 v11, v138, v139
	s_waitcnt lgkmcnt(11)
	v_mfma_f32_32x32x16_bf16 v[112:127], v[156:159], v[176:179], v[112:127]
	ds_read_b64_tr_b16 v[136:137], v206 offset:46080
	ds_read_b64_tr_b16 v[138:139], v206 offset:46592
	s_waitcnt lgkmcnt(12)
	v_mfma_f32_32x32x16_bf16 v[80:95], v[180:183], v[176:179], v[80:95]
	v_add_f32_e32 v251, v97, v251
	v_add_f32_e32 v252, v98, v252
	v_add_f32_e32 v253, v99, v253
	v_add_f32_e32 v250, v100, v250
	v_cvt_pk_bf16_f32 v12, v140, v141
	v_cvt_pk_bf16_f32 v13, v142, v143
	ds_read_b64_tr_b16 v[140:141], v206 offset:43008
	ds_read_b64_tr_b16 v[142:143], v206 offset:43520
	v_add_f32_e32 v251, v101, v251
	v_add_f32_e32 v252, v102, v252
	v_add_f32_e32 v253, v103, v253
	v_add_f32_e32 v250, v104, v250
	v_cvt_pk_bf16_f32 v6, v96, v97
	v_cvt_pk_bf16_f32 v7, v98, v99
	s_waitcnt lgkmcnt(13)
	v_mfma_f32_32x32x16_bf16 v[112:127], v[184:187], v[168:171], v[112:127]
	ds_read_b64_tr_b16 v[96:97], v206 offset:47104
	ds_read_b64_tr_b16 v[98:99], v206 offset:47616
	s_waitcnt lgkmcnt(14)
	v_mfma_f32_32x32x16_bf16 v[80:95], v[188:191], v[168:171], v[80:95]
	v_add_f32_e32 v251, v105, v251
	v_add_f32_e32 v252, v106, v252
	v_add_f32_e32 v253, v107, v253
	v_add_f32_e32 v250, v108, v250
	v_cvt_pk_bf16_f32 v8, v100, v101
	v_cvt_pk_bf16_f32 v9, v102, v103
	ds_read_b64_tr_b16 v[100:101], v206 offset:44032
	ds_read_b64_tr_b16 v[102:103], v206 offset:44544
	v_add_f32_e32 v251, v109, v251
	v_add_f32_e32 v252, v110, v252
	v_add_f32_e32 v253, v111, v253
	v_add_f32_e32 v250, v251, v250
	v_cvt_pk_bf16_f32 v2, v104, v105
	v_cvt_pk_bf16_f32 v3, v106, v107
	s_waitcnt lgkmcnt(14)
	v_mfma_f32_32x32x16_bf16 v[112:127], v[148:151], v[164:167], v[112:127]
	ds_read_b64_tr_b16 v[104:105], v206 offset:48128
	ds_read_b64_tr_b16 v[106:107], v206 offset:48640
	v_mfma_f32_32x32x16_bf16 v[80:95], v[144:147], v[164:167], v[80:95]
	v_add_f32_e32 v252, v253, v252
	v_add_f32_e32 v14, v252, v250
	v_cvt_pk_bf16_f32 v4, v108, v109
	v_cvt_pk_bf16_f32 v5, v110, v111
	s_nop 0
	v_add_f32_e32 v185, v0, v14
	s_waitcnt lgkmcnt(14)
	v_mfma_f32_32x32x16_bf16 v[48:63], v[160:163], v[192:195], v[48:63]
	s_nop 0
	v_exp_f32_e32 v112, v112
	v_exp_f32_e32 v113, v113
	v_exp_f32_e32 v114, v114
	v_exp_f32_e32 v115, v115
	s_waitcnt lgkmcnt(12)
	v_mfma_f32_32x32x16_bf16 v[64:79], v[160:163], v[128:131], v[64:79]
	v_exp_f32_e32 v116, v116
	v_exp_f32_e32 v117, v117
	v_exp_f32_e32 v118, v118
	v_exp_f32_e32 v119, v119
	ds_read_b128 v[148:151], v208 offset:24576
	ds_read_b128 v[186:189], v208 offset:26624
	s_waitcnt lgkmcnt(12)
	v_mfma_f32_32x32x16_bf16 v[48:63], v[10:13], v[132:135], v[48:63]
	v_exp_f32_e32 v120, v120
	v_exp_f32_e32 v121, v121
	v_exp_f32_e32 v122, v122
	v_exp_f32_e32 v123, v123
	ds_read_b128 v[190:193], v209 offset:24576
	ds_read_b128 v[194:197], v209 offset:26624
	s_waitcnt lgkmcnt(12)
	v_mfma_f32_32x32x16_bf16 v[64:79], v[10:13], v[136:139], v[64:79]
	v_exp_f32_e32 v124, v124
	v_exp_f32_e32 v125, v125
	v_exp_f32_e32 v126, v126
	v_exp_f32_e32 v127, v127
	ds_read_b128 v[210:213], v208 offset:28672
	ds_read_b128 v[180:183], v208 offset:30720
	s_waitcnt lgkmcnt(12)
	v_mfma_f32_32x32x16_bf16 v[48:63], v[6:9], v[140:143], v[48:63]
	v_exp_f32_e32 v80, v80
	v_exp_f32_e32 v81, v81
	v_exp_f32_e32 v82, v82
	v_exp_f32_e32 v83, v83
	ds_read_b128 v[156:159], v209 offset:28672
	ds_read_b128 v[152:155], v209 offset:30720
	s_waitcnt lgkmcnt(12)
	v_mfma_f32_32x32x16_bf16 v[64:79], v[6:9], v[96:99], v[64:79]
	v_exp_f32_e32 v84, v84
	v_exp_f32_e32 v85, v85
	v_exp_f32_e32 v86, v86
	v_exp_f32_e32 v87, v87
	s_waitcnt lgkmcnt(10)
	v_mfma_f32_32x32x16_bf16 v[48:63], v[2:5], v[100:103], v[48:63]
	v_exp_f32_e32 v88, v88
	v_exp_f32_e32 v89, v89
	v_exp_f32_e32 v90, v90
	v_exp_f32_e32 v91, v91
	s_waitcnt lgkmcnt(8)
	v_mfma_f32_32x32x16_bf16 v[64:79], v[2:5], v[104:107], v[64:79]
	v_exp_f32_e32 v92, v92
	v_exp_f32_e32 v93, v93
	v_exp_f32_e32 v94, v94
	v_exp_f32_e32 v95, v95
	v_lshrrev_b32_e32 v184, 3, v203
	v_or_b32_e32 v2, s4, v184
	v_mov_b32_e32 v3, s5
	v_lshlrev_b64 v[14:15], 11, v[2:3]
	v_lshl_add_u64 v[2:3], s[48:49], 0, v[14:15]
	s_lshl_b32 s8, s26, 1
	v_and_b32_e32 v0, 56, v207
	v_lshl_add_u64 v[2:3], v[2:3], 0, s[8:9]
	v_lshlrev_b32_e32 v0, 1, v0
	v_lshl_add_u64 v[2:3], v[2:3], 0, v[0:1]
	v_add_co_u32_e32 v6, vcc, s67, v2
	s_waitcnt vmcnt(0) lgkmcnt(0)
	s_barrier
	s_nop 1
	v_addc_co_u32_e32 v7, vcc, 0, v3, vcc
	global_load_dwordx4 v[140:143], v[2:3], off nt
	global_load_dwordx4 v[136:139], v[6:7], off nt
	v_add_co_u32_e32 v6, vcc, s66, v2
	s_nop 1
	v_addc_co_u32_e32 v7, vcc, 0, v3, vcc
	v_add_co_u32_e32 v2, vcc, s63, v2
	s_nop 1
	v_addc_co_u32_e32 v3, vcc, 0, v3, vcc
	global_load_dwordx4 v[132:135], v[6:7], off nt
	global_load_dwordx4 v[128:131], v[2:3], off nt
	ds_read_b64_tr_b16 v[144:145], v206 offset:49152
	ds_read_b64_tr_b16 v[146:147], v206 offset:49664
	v_add_f32_e32 v250, v112, v113
	v_add_f32_e32 v251, v114, v115
	v_add_f32_e32 v252, v116, v117
	v_add_f32_e32 v253, v118, v119
	v_add_f32_e32 v250, v120, v250
	v_cvt_pk_bf16_f32 v160, v112, v113
	v_cvt_pk_bf16_f32 v161, v114, v115
	s_waitcnt lgkmcnt(9)
	v_mfma_f32_32x32x16_bf16 v[96:111], v[148:151], v[172:175], v[32:47]
	ds_read_b64_tr_b16 v[112:113], v206 offset:53248
	ds_read_b64_tr_b16 v[114:115], v206 offset:53760
	v_add_f32_e32 v251, v121, v251
	v_add_f32_e32 v252, v122, v252
	v_add_f32_e32 v253, v123, v253
	v_add_f32_e32 v250, v124, v250
	v_cvt_pk_bf16_f32 v162, v116, v117
	v_cvt_pk_bf16_f32 v163, v118, v119
	s_waitcnt lgkmcnt(10)
	v_mfma_f32_32x32x16_bf16 v[32:47], v[186:189], v[172:175], v[32:47]
	ds_read_b64_tr_b16 v[148:149], v206 offset:50176
	ds_read_b64_tr_b16 v[150:151], v206 offset:50688
	v_add_f32_e32 v251, v125, v251
	v_add_f32_e32 v252, v126, v252
	v_add_f32_e32 v253, v127, v253
	v_add_f32_e32 v250, v80, v250
	v_cvt_pk_bf16_f32 v10, v120, v121
	v_cvt_pk_bf16_f32 v11, v122, v123
	s_waitcnt lgkmcnt(11)
	v_mfma_f32_32x32x16_bf16 v[96:111], v[190:193], v[176:179], v[96:111]
	ds_read_b64_tr_b16 v[116:117], v206 offset:54272
	ds_read_b64_tr_b16 v[118:119], v206 offset:54784
	v_add_f32_e32 v251, v81, v251
	v_add_f32_e32 v252, v82, v252
	v_add_f32_e32 v253, v83, v253
	v_add_f32_e32 v250, v84, v250
	v_cvt_pk_bf16_f32 v12, v124, v125
	v_cvt_pk_bf16_f32 v13, v126, v127
	s_waitcnt lgkmcnt(12)
	v_mfma_f32_32x32x16_bf16 v[32:47], v[194:197], v[176:179], v[32:47]
	ds_read_b64_tr_b16 v[120:121], v206 offset:51200
	ds_read_b64_tr_b16 v[122:123], v206 offset:51712
	v_add_f32_e32 v251, v85, v251
	v_add_f32_e32 v252, v86, v252
	v_add_f32_e32 v253, v87, v253
	v_add_f32_e32 v250, v88, v250
	v_cvt_pk_bf16_f32 v6, v80, v81
	v_cvt_pk_bf16_f32 v7, v82, v83
	s_waitcnt lgkmcnt(13)
	v_mfma_f32_32x32x16_bf16 v[96:111], v[210:213], v[168:171], v[96:111]
	ds_read_b64_tr_b16 v[80:81], v206 offset:55296
	ds_read_b64_tr_b16 v[82:83], v206 offset:55808
	v_add_f32_e32 v251, v89, v251
	v_add_f32_e32 v252, v90, v252
	v_add_f32_e32 v253, v91, v253
	v_add_f32_e32 v250, v92, v250
	v_cvt_pk_bf16_f32 v8, v84, v85
	v_cvt_pk_bf16_f32 v9, v86, v87
	s_waitcnt lgkmcnt(14)
	v_mfma_f32_32x32x16_bf16 v[32:47], v[180:183], v[168:171], v[32:47]
	ds_read_b64_tr_b16 v[124:125], v206 offset:52224
	ds_read_b64_tr_b16 v[126:127], v206 offset:52736
	v_add_f32_e32 v251, v93, v251
	v_add_f32_e32 v252, v94, v252
	v_add_f32_e32 v253, v95, v253
	v_add_f32_e32 v250, v251, v250
	v_cvt_pk_bf16_f32 v2, v88, v89
	v_cvt_pk_bf16_f32 v3, v90, v91
	s_waitcnt lgkmcnt(14)
	v_mfma_f32_32x32x16_bf16 v[96:111], v[156:159], v[164:167], v[96:111]
	ds_read_b64_tr_b16 v[84:85], v206 offset:56320
	ds_read_b64_tr_b16 v[86:87], v206 offset:56832
	v_add_f32_e32 v252, v253, v252
	v_add_f32_e32 v88, v252, v250
	v_cvt_pk_bf16_f32 v4, v92, v93
	v_cvt_pk_bf16_f32 v5, v94, v95
	v_mfma_f32_32x32x16_bf16 v[32:47], v[152:155], v[164:167], v[32:47]
	s_nop 4
	v_exp_f32_e32 v96, v96
	v_exp_f32_e32 v97, v97
	v_exp_f32_e32 v98, v98
	v_exp_f32_e32 v99, v99
	s_nop 0
	v_exp_f32_e32 v100, v100
	v_exp_f32_e32 v101, v101
	v_exp_f32_e32 v102, v102
	v_exp_f32_e32 v103, v103
	s_nop 0
	v_exp_f32_e32 v104, v104
	v_exp_f32_e32 v105, v105
	v_exp_f32_e32 v106, v106
	v_exp_f32_e32 v107, v107
	s_nop 0
	v_exp_f32_e32 v108, v108
	v_exp_f32_e32 v109, v109
	v_exp_f32_e32 v110, v110
	v_exp_f32_e32 v111, v111
	v_exp_f32_e32 v32, v32
	v_exp_f32_e32 v33, v33
	v_exp_f32_e32 v34, v34
	v_exp_f32_e32 v35, v35
	s_nop 0
	v_exp_f32_e32 v36, v36
	v_exp_f32_e32 v37, v37
	v_exp_f32_e32 v38, v38
	v_exp_f32_e32 v39, v39
	s_nop 0
	v_exp_f32_e32 v40, v40
	v_exp_f32_e32 v41, v41
	v_exp_f32_e32 v42, v42
	v_exp_f32_e32 v43, v43
	s_nop 0
	v_exp_f32_e32 v44, v44
	v_exp_f32_e32 v45, v45
	v_exp_f32_e32 v46, v46
	v_exp_f32_e32 v47, v47
	s_waitcnt lgkmcnt(14)
	v_mfma_f32_32x32x16_bf16 v[48:63], v[160:163], v[144:147], v[48:63]
	v_add_f32_e32 v250, v96, v97
	v_add_f32_e32 v251, v98, v99
	v_add_f32_e32 v252, v100, v101
	v_add_f32_e32 v253, v102, v103
	v_add_f32_e32 v250, v104, v250
	v_add_f32_e32 v251, v105, v251
	v_add_f32_e32 v252, v106, v252
	s_waitcnt lgkmcnt(12)
	v_mfma_f32_32x32x16_bf16 v[64:79], v[160:163], v[112:115], v[64:79]
	v_add_f32_e32 v253, v107, v253
	v_add_f32_e32 v250, v108, v250
	v_add_f32_e32 v251, v109, v251
	v_add_f32_e32 v252, v110, v252
	v_add_f32_e32 v253, v111, v253
	v_add_f32_e32 v250, v32, v250
	v_add_f32_e32 v251, v33, v251
	s_waitcnt lgkmcnt(10)
	v_mfma_f32_32x32x16_bf16 v[48:63], v[10:13], v[148:151], v[48:63]
	v_add_f32_e32 v252, v34, v252
	v_add_f32_e32 v253, v35, v253
	v_add_f32_e32 v250, v36, v250
	v_add_f32_e32 v251, v37, v251
	v_add_f32_e32 v252, v38, v252
	v_add_f32_e32 v253, v39, v253
	v_add_f32_e32 v250, v40, v250
	s_waitcnt lgkmcnt(8)
	v_mfma_f32_32x32x16_bf16 v[64:79], v[10:13], v[116:119], v[64:79]
	v_add_f32_e32 v251, v41, v251
	v_add_f32_e32 v252, v42, v252
	v_add_f32_e32 v253, v43, v253
	v_add_f32_e32 v250, v44, v250
	v_add_f32_e32 v251, v45, v251
	v_add_f32_e32 v252, v46, v252
	v_add_f32_e32 v253, v47, v253
	s_waitcnt lgkmcnt(6)
	v_mfma_f32_32x32x16_bf16 v[48:63], v[6:9], v[120:123], v[48:63]
	v_add_f32_e32 v250, v251, v250
	v_add_f32_e32 v252, v253, v252
	v_add_f32_e32 v89, v252, v250
	v_add_f32_e32 v88, v185, v88
	v_add_f32_e32 v88, v88, v89
	v_cvt_pk_bf16_f32 v90, v96, v97
	v_cvt_pk_bf16_f32 v91, v98, v99
	s_waitcnt lgkmcnt(4)
	v_mfma_f32_32x32x16_bf16 v[64:79], v[6:9], v[80:83], v[64:79]
	v_cvt_pk_bf16_f32 v92, v100, v101
	v_cvt_pk_bf16_f32 v93, v102, v103
	v_cvt_pk_bf16_f32 v10, v104, v105
	v_cvt_pk_bf16_f32 v11, v106, v107
	v_cvt_pk_bf16_f32 v12, v108, v109
	v_cvt_pk_bf16_f32 v13, v110, v111
	v_cvt_pk_bf16_f32 v6, v32, v33
	s_waitcnt lgkmcnt(2)
	v_mfma_f32_32x32x16_bf16 v[48:63], v[2:5], v[124:127], v[48:63]
	v_cvt_pk_bf16_f32 v7, v34, v35
	v_cvt_pk_bf16_f32 v8, v36, v37
	v_cvt_pk_bf16_f32 v9, v38, v39
	v_cvt_pk_bf16_f32 v32, v40, v41
	v_cvt_pk_bf16_f32 v33, v42, v43
	v_cvt_pk_bf16_f32 v34, v44, v45
	v_cvt_pk_bf16_f32 v35, v46, v47
	s_waitcnt lgkmcnt(0)
	v_mfma_f32_32x32x16_bf16 v[64:79], v[2:5], v[84:87], v[64:79]
	v_add_u32_e32 v2, s6, v204
	v_add3_u32 v84, v2, v202, v205
	ds_read_b64_tr_b16 v[2:3],v84 offset:0
	ds_read_b64_tr_b16 v[4:5],v84 offset:512
	ds_read_b64_tr_b16 v[36:37],v84 offset:1024
	ds_read_b64_tr_b16 v[38:39],v84 offset:1536
	ds_read_b64_tr_b16 v[40:41],v84 offset:2048
	ds_read_b64_tr_b16 v[42:43],v84 offset:2560
	ds_read_b64_tr_b16 v[44:45],v84 offset:3072
	ds_read_b64_tr_b16 v[46:47],v84 offset:3584
	s_waitcnt lgkmcnt(0)
	s_nop 0
	v_mfma_f32_32x32x16_bf16 v[48:63], v[90:93], v[2:5], v[48:63]
	ds_read_b64_tr_b16 v[2:3],v84 offset:4096
	ds_read_b64_tr_b16 v[4:5],v84 offset:4608
	v_mfma_f32_32x32x16_bf16 v[48:63], v[10:13], v[36:39], v[48:63]
	ds_read_b64_tr_b16 v[36:37],v84 offset:5120
	ds_read_b64_tr_b16 v[38:39],v84 offset:5632
	v_mfma_f32_32x32x16_bf16 v[48:63], v[6:9], v[40:43], v[48:63]
	ds_read_b64_tr_b16 v[40:41],v84 offset:6144
	ds_read_b64_tr_b16 v[42:43],v84 offset:6656
	ds_read_b64_tr_b16 v[80:81],v84 offset:7168
	ds_read_b64_tr_b16 v[82:83],v84 offset:7680
	s_waitcnt lgkmcnt(0)
	v_mfma_f32_32x32x16_bf16 v[48:63], v[32:35], v[44:47], v[48:63]
	v_mfma_f32_32x32x16_bf16 v[64:79], v[90:93], v[2:5], v[64:79]
	v_mov_b32_e32 v2, v88
	s_nop 1
	v_permlane32_swap_b32_e32 v88, v2
	v_cmp_gt_u32_e32 vcc, 32, v203
	v_mfma_f32_32x32x16_bf16 v[64:79], v[10:13], v[36:39], v[64:79]
	v_mfma_f32_32x32x16_bf16 v[64:79], v[6:9], v[40:43], v[64:79]
	v_mfma_f32_32x32x16_bf16 v[64:79], v[32:35], v[80:83], v[64:79]
	s_and_saveexec_b64 s[6:7], vcc
	v_lshl_add_u32 v3, v200, 2, s31
	v_add_f32_e32 v2, v88, v2
	ds_write_b32 v3, v2 offset:128
	s_or_b64 exec, exec, s[6:7]
	s_waitcnt lgkmcnt(0)
	v_lshl_add_u32 v10, v201, 4, s31
	ds_read_b128 v[2:5], v10 offset:128
	ds_read_b128 v[6:9], v10 offset:160
	s_lshl_b32 s6, s27, 12
	s_add_i32 s6, s6, 0
	s_add_i32 s6, s6, 0x10800
	s_waitcnt lgkmcnt(1)
	v_rcp_f32_e32 v11, v2
	v_rcp_f32_e32 v12, v3
	v_rcp_f32_e32 v13, v4
	v_rcp_f32_e32 v32, v5
	s_waitcnt lgkmcnt(0)
	v_rcp_f32_e32 v33, v6
	ds_read_b128 v[2:5], v10 offset:192
	v_rcp_f32_e32 v34, v7
	v_rcp_f32_e32 v35, v8
	v_rcp_f32_e32 v36, v9
	ds_read_b128 v[6:9], v10 offset:224
	v_lshlrev_b32_e32 v10, 9, v201
	v_lshlrev_b32_e32 v37, 1, v200
	v_add3_u32 v10, s6, v10, v37
	v_mul_f32_e32 v37, v48, v11
	v_mul_f32_e32 v11, v64, v11
	v_cvt_pk_bf16_f32 v11, v11, s0
	ds_write_b16 v10, v11 offset:64
	v_mul_f32_e32 v11, v49, v12
	v_cvt_pk_bf16_f32 v11, v11, s0
	ds_write_b16 v10, v11 offset:128
	v_mul_f32_e32 v11, v65, v12
	v_cvt_pk_bf16_f32 v11, v11, s0
	ds_write_b16 v10, v11 offset:192
	v_mul_f32_e32 v11, v50, v13
	v_cvt_pk_bf16_f32 v11, v11, s0
	ds_write_b16 v10, v11 offset:256
	v_mul_f32_e32 v11, v66, v13
	v_cvt_pk_bf16_f32 v11, v11, s0
	ds_write_b16 v10, v11 offset:320
	v_mul_f32_e32 v11, v51, v32
	v_cvt_pk_bf16_f32 v11, v11, s0
	ds_write_b16 v10, v11 offset:384
	v_mul_f32_e32 v11, v67, v32
	v_cvt_pk_bf16_f32 v11, v11, s0
	ds_write_b16 v10, v11 offset:448
	v_mul_f32_e32 v11, v52, v33
	v_cvt_pk_bf16_f32 v11, v11, s0
	ds_write_b16 v10, v11 offset:1024
	v_mul_f32_e32 v11, v68, v33
	v_cvt_pk_bf16_f32 v11, v11, s0
	ds_write_b16 v10, v11 offset:1088
	v_mul_f32_e32 v11, v53, v34
	v_cvt_pk_bf16_f32 v11, v11, s0
	ds_write_b16 v10, v11 offset:1152
	v_mul_f32_e32 v11, v69, v34
	v_cvt_pk_bf16_f32 v11, v11, s0
	ds_write_b16 v10, v11 offset:1216
	v_mul_f32_e32 v11, v54, v35
	v_cvt_pk_bf16_f32 v11, v11, s0
	ds_write_b16 v10, v11 offset:1280
	v_mul_f32_e32 v11, v70, v35
	v_cvt_pk_bf16_f32 v11, v11, s0
	s_waitcnt lgkmcnt(13)
	v_rcp_f32_e32 v2, v2
	ds_write_b16 v10, v11 offset:1344
	v_mul_f32_e32 v11, v55, v36
	v_cvt_pk_bf16_f32 v11, v11, s0
	v_rcp_f32_e32 v3, v3
	ds_write_b16 v10, v11 offset:1408
	v_mul_f32_e32 v11, v71, v36
	v_cvt_pk_bf16_f32 v11, v11, s0
	ds_write_b16 v10, v11 offset:1472
	v_mul_f32_e32 v11, v56, v2
	v_mul_f32_e32 v2, v72, v2
	v_cvt_pk_bf16_f32 v2, v2, s0
	v_rcp_f32_e32 v4, v4
	ds_write_b16 v10, v2 offset:2112
	v_mul_f32_e32 v2, v57, v3
	v_cvt_pk_bf16_f32 v2, v2, s0
	ds_write_b16 v10, v2 offset:2176
	v_mul_f32_e32 v2, v73, v3
	v_cvt_pk_bf16_f32 v2, v2, s0
	v_rcp_f32_e32 v5, v5
	ds_write_b16 v10, v2 offset:2240
	v_mul_f32_e32 v2, v58, v4
	v_cvt_pk_bf16_f32 v2, v2, s0
	ds_write_b16 v10, v2 offset:2304
	v_mul_f32_e32 v2, v74, v4
	v_cvt_pk_bf16_f32 v2, v2, s0
	s_waitcnt lgkmcnt(14)
	v_rcp_f32_e32 v6, v6
	ds_write_b16 v10, v2 offset:2368
	v_mul_f32_e32 v2, v59, v5
	v_cvt_pk_bf16_f32 v2, v2, s0
	ds_write_b16 v10, v2 offset:2432
	v_mul_f32_e32 v2, v75, v5
	v_cvt_pk_bf16_f32 v2, v2, s0
	v_rcp_f32_e32 v7, v7
	ds_write_b16 v10, v2 offset:2496
	v_mul_f32_e32 v2, v60, v6
	v_cvt_pk_bf16_f32 v2, v2, s0
	ds_write_b16 v10, v2 offset:3072
	v_mul_f32_e32 v2, v76, v6
	v_cvt_pk_bf16_f32 v2, v2, s0
	v_rcp_f32_e32 v8, v8
	ds_write_b16 v10, v2 offset:3136
	v_mul_f32_e32 v2, v61, v7
	v_cvt_pk_bf16_f32 v2, v2, s0
	ds_write_b16 v10, v2 offset:3200
	v_mul_f32_e32 v2, v77, v7
	v_cvt_pk_bf16_f32 v2, v2, s0
	v_rcp_f32_e32 v9, v9
	ds_write_b16 v10, v2 offset:3264
	v_mul_f32_e32 v2, v62, v8
	v_cvt_pk_bf16_f32 v2, v2, s0
	ds_write_b16 v10, v2 offset:3328
	v_mul_f32_e32 v2, v78, v8
	v_cvt_pk_bf16_f32 v2, v2, s0
	ds_write_b16 v10, v2 offset:3392
	v_mul_f32_e32 v2, v63, v9
	s_waitcnt vmcnt(3)
	v_lshlrev_b32_e32 v12, 16, v140
	v_cvt_pk_bf16_f32 v2, v2, s0
	v_and_b32_e32 v13, 0xffff0000, v140
	v_mul_f32_e32 v4, 0xbfb8aa3b, v12
	ds_write_b16 v10, v2 offset:3456
	v_mul_f32_e32 v2, v79, v9
	v_exp_f32_e32 v8, v4
	v_mul_f32_e32 v4, 0xbfb8aa3b, v13
	v_cvt_pk_bf16_f32 v37, v37, s0
	v_cvt_pk_bf16_f32 v11, v11, s0
	v_cvt_pk_bf16_f32 v2, v2, s0
	v_add_u32_e32 v36, s6, v0
	s_add_u32 s6, s50, s8
	v_exp_f32_e32 v9, v4
	ds_write_b16 v10, v37
	ds_write_b16 v10, v11 offset:2048
	ds_write_b16 v10, v2 offset:3520
	s_addc_u32 s7, s51, 0
	s_waitcnt lgkmcnt(0)
	v_lshl_add_u64 v[2:3], s[6:7], 0, v[0:1]
	v_lshl_add_u32 v0, v184, 7, v36
	ds_read_b128 v[4:7], v0
	v_add_f32_e32 v0, 1.0, v8
	v_rcp_f32_e32 v32, v0
	v_add_f32_e32 v0, 1.0, v9
	v_rcp_f32_e32 v33, v0
	s_waitcnt lgkmcnt(0)
	v_lshlrev_b32_e32 v34, 16, v4
	v_and_b32_e32 v35, 0xffff0000, v4
	v_or_b32_e32 v0, 8, v184
	v_pk_mul_f32 v[12:13], v[32:33], v[12:13]
	v_lshlrev_b32_e32 v32, 16, v141
	v_and_b32_e32 v33, 0xffff0000, v141
	v_mul_f32_e32 v4, 0xbfb8aa3b, v32
	v_exp_f32_e32 v4, v4
	v_mul_f32_e32 v37, 0xbfb8aa3b, v33
	v_exp_f32_e32 v37, v37
	v_pk_mul_f32 v[12:13], v[12:13], v[34:35]
	v_add_f32_e32 v4, 1.0, v4
	v_rcp_f32_e32 v34, v4
	v_add_f32_e32 v4, 1.0, v37
	v_rcp_f32_e32 v35, v4
	v_cvt_pk_bf16_f32 v4, v12, v13
	v_lshlrev_b32_e32 v12, 16, v5
	v_and_b32_e32 v13, 0xffff0000, v5
	v_pk_mul_f32 v[32:33], v[34:35], v[32:33]
	v_lshlrev_b32_e32 v34, 16, v142
	v_and_b32_e32 v35, 0xffff0000, v142
	v_mul_f32_e32 v5, 0xbfb8aa3b, v34
	v_exp_f32_e32 v5, v5
	v_mul_f32_e32 v37, 0xbfb8aa3b, v35
	v_exp_f32_e32 v37, v37
	v_pk_mul_f32 v[12:13], v[32:33], v[12:13]
	v_add_f32_e32 v5, 1.0, v5
	v_rcp_f32_e32 v32, v5
	v_add_f32_e32 v5, 1.0, v37
	v_rcp_f32_e32 v33, v5
	v_cvt_pk_bf16_f32 v5, v12, v13
	v_lshlrev_b32_e32 v12, 16, v6
	v_and_b32_e32 v13, 0xffff0000, v6
	v_pk_mul_f32 v[32:33], v[32:33], v[34:35]
	v_lshlrev_b32_e32 v34, 16, v143
	v_and_b32_e32 v35, 0xffff0000, v143
	v_mul_f32_e32 v6, 0xbfb8aa3b, v34
	v_exp_f32_e32 v6, v6
	v_mul_f32_e32 v37, 0xbfb8aa3b, v35
	v_exp_f32_e32 v37, v37
	v_pk_mul_f32 v[12:13], v[32:33], v[12:13]
	v_add_f32_e32 v6, 1.0, v6
	v_rcp_f32_e32 v32, v6
	v_add_f32_e32 v6, 1.0, v37
	v_rcp_f32_e32 v33, v6
	v_cvt_pk_bf16_f32 v6, v12, v13
	v_lshlrev_b32_e32 v12, 16, v7
	v_and_b32_e32 v13, 0xffff0000, v7
	v_pk_mul_f32 v[32:33], v[32:33], v[34:35]
	v_lshl_add_u32 v8, v0, 7, v36
	v_pk_mul_f32 v[12:13], v[32:33], v[12:13]
	ds_read_b128 v[8:11], v8
	v_cvt_pk_bf16_f32 v7, v12, v13
	v_lshl_add_u64 v[12:13], v[2:3], 0, v[14:15]
	global_store_dwordx4 v[12:13], v[4:7], off
	s_waitcnt lgkmcnt(0)
	v_lshlrev_b32_e32 v14, 16, v8
	s_waitcnt vmcnt(3)
	v_lshlrev_b32_e32 v6, 16, v136
	v_and_b32_e32 v7, 0xffff0000, v136
	v_mul_f32_e32 v4, 0xbfb8aa3b, v6
	v_exp_f32_e32 v5, v4
	v_mul_f32_e32 v4, 0xbfb8aa3b, v7
	v_exp_f32_e32 v13, v4
	v_or_b32_e32 v4, s4, v0
	v_add_f32_e32 v0, 1.0, v5
	v_rcp_f32_e32 v12, v0
	v_add_f32_e32 v0, 1.0, v13
	v_rcp_f32_e32 v13, v0
	v_and_b32_e32 v15, 0xffff0000, v8
	v_mov_b32_e32 v5, s5
	v_pk_mul_f32 v[6:7], v[12:13], v[6:7]
	v_lshlrev_b32_e32 v12, 16, v137
	v_and_b32_e32 v13, 0xffff0000, v137
	v_mul_f32_e32 v0, 0xbfb8aa3b, v12
	v_exp_f32_e32 v0, v0
	v_mul_f32_e32 v8, 0xbfb8aa3b, v13
	v_exp_f32_e32 v8, v8
	v_pk_mul_f32 v[6:7], v[6:7], v[14:15]
	v_add_f32_e32 v0, 1.0, v0
	v_rcp_f32_e32 v14, v0
	v_add_f32_e32 v0, 1.0, v8
	v_rcp_f32_e32 v15, v0
	v_cvt_pk_bf16_f32 v6, v6, v7
	v_lshlrev_b32_e32 v8, 16, v9
	v_and_b32_e32 v9, 0xffff0000, v9
	v_pk_mul_f32 v[12:13], v[14:15], v[12:13]
	v_lshlrev_b32_e32 v14, 16, v138
	v_and_b32_e32 v15, 0xffff0000, v138
	v_mul_f32_e32 v0, 0xbfb8aa3b, v14
	v_exp_f32_e32 v0, v0
	v_mul_f32_e32 v7, 0xbfb8aa3b, v15
	v_exp_f32_e32 v7, v7
	v_pk_mul_f32 v[8:9], v[12:13], v[8:9]
	v_add_f32_e32 v0, 1.0, v0
	v_rcp_f32_e32 v12, v0
	v_add_f32_e32 v0, 1.0, v7
	v_rcp_f32_e32 v13, v0
	v_cvt_pk_bf16_f32 v7, v8, v9
	v_lshlrev_b32_e32 v8, 16, v10
	v_and_b32_e32 v9, 0xffff0000, v10
	v_pk_mul_f32 v[12:13], v[12:13], v[14:15]
	v_lshlrev_b32_e32 v14, 16, v139
	v_and_b32_e32 v15, 0xffff0000, v139
	v_mul_f32_e32 v0, 0xbfb8aa3b, v14
	v_exp_f32_e32 v0, v0
	v_mul_f32_e32 v10, 0xbfb8aa3b, v15
	v_exp_f32_e32 v10, v10
	v_pk_mul_f32 v[8:9], v[12:13], v[8:9]
	v_add_f32_e32 v0, 1.0, v0
	v_rcp_f32_e32 v12, v0
	v_add_f32_e32 v0, 1.0, v10
	v_rcp_f32_e32 v13, v0
	v_lshlrev_b32_e32 v10, 16, v11
	v_and_b32_e32 v11, 0xffff0000, v11
	v_cvt_pk_bf16_f32 v8, v8, v9
	v_pk_mul_f32 v[12:13], v[12:13], v[14:15]
	v_or_b32_e32 v0, 16, v184
	v_pk_mul_f32 v[10:11], v[12:13], v[10:11]
	s_waitcnt vmcnt(2)
	v_lshlrev_b32_e32 v14, 16, v132
	v_cvt_pk_bf16_f32 v9, v10, v11
	v_lshlrev_b64 v[10:11], 11, v[4:5]
	v_lshl_add_u64 v[10:11], v[2:3], 0, v[10:11]
	v_lshl_add_u32 v4, v0, 7, v36
	global_store_dwordx4 v[10:11], v[6:9], off
	ds_read_b128 v[6:9], v4
	v_and_b32_e32 v15, 0xffff0000, v132
	v_mul_f32_e32 v4, 0xbfb8aa3b, v14
	v_exp_f32_e32 v10, v4
	v_mul_f32_e32 v4, 0xbfb8aa3b, v15
	v_exp_f32_e32 v11, v4
	v_or_b32_e32 v4, s4, v0
	v_add_f32_e32 v0, 1.0, v10
	v_rcp_f32_e32 v32, v0
	v_add_f32_e32 v0, 1.0, v11
	v_rcp_f32_e32 v33, v0
	v_or_b32_e32 v0, 24, v184
	s_waitcnt lgkmcnt(0)
	v_lshlrev_b32_e32 v34, 16, v6
	v_and_b32_e32 v35, 0xffff0000, v6
	v_pk_mul_f32 v[14:15], v[32:33], v[14:15]
	v_lshlrev_b32_e32 v32, 16, v133
	v_and_b32_e32 v33, 0xffff0000, v133
	v_mul_f32_e32 v6, 0xbfb8aa3b, v32
	v_lshl_add_u32 v10, v0, 7, v36
	v_exp_f32_e32 v6, v6
	v_mul_f32_e32 v36, 0xbfb8aa3b, v33
	v_exp_f32_e32 v36, v36
	v_pk_mul_f32 v[14:15], v[14:15], v[34:35]
	v_add_f32_e32 v6, 1.0, v6
	v_rcp_f32_e32 v34, v6
	v_add_f32_e32 v6, 1.0, v36
	v_rcp_f32_e32 v35, v6
	v_cvt_pk_bf16_f32 v6, v14, v15
	v_lshlrev_b32_e32 v14, 16, v7
	v_and_b32_e32 v15, 0xffff0000, v7
	v_pk_mul_f32 v[32:33], v[34:35], v[32:33]
	v_lshlrev_b32_e32 v34, 16, v134
	v_and_b32_e32 v35, 0xffff0000, v134
	v_mul_f32_e32 v7, 0xbfb8aa3b, v34
	v_exp_f32_e32 v7, v7
	v_mul_f32_e32 v36, 0xbfb8aa3b, v35
	v_exp_f32_e32 v36, v36
	v_pk_mul_f32 v[14:15], v[32:33], v[14:15]
	v_add_f32_e32 v7, 1.0, v7
	v_rcp_f32_e32 v32, v7
	v_add_f32_e32 v7, 1.0, v36
	v_rcp_f32_e32 v33, v7
	v_cvt_pk_bf16_f32 v7, v14, v15
	v_lshlrev_b32_e32 v14, 16, v8
	v_and_b32_e32 v15, 0xffff0000, v8
	v_pk_mul_f32 v[32:33], v[32:33], v[34:35]
	v_lshlrev_b32_e32 v34, 16, v135
	v_and_b32_e32 v35, 0xffff0000, v135
	v_mul_f32_e32 v8, 0xbfb8aa3b, v34
	v_exp_f32_e32 v8, v8
	v_mul_f32_e32 v36, 0xbfb8aa3b, v35
	v_exp_f32_e32 v36, v36
	v_pk_mul_f32 v[14:15], v[32:33], v[14:15]
	v_add_f32_e32 v8, 1.0, v8
	v_rcp_f32_e32 v32, v8
	v_add_f32_e32 v8, 1.0, v36
	v_rcp_f32_e32 v33, v8
	v_cvt_pk_bf16_f32 v8, v14, v15
	v_lshlrev_b32_e32 v14, 16, v9
	v_and_b32_e32 v15, 0xffff0000, v9
	v_pk_mul_f32 v[32:33], v[32:33], v[34:35]
	ds_read_b128 v[10:13], v10
	v_pk_mul_f32 v[14:15], v[32:33], v[14:15]
	s_waitcnt vmcnt(2)
	v_lshlrev_b32_e32 v32, 16, v128
	v_cvt_pk_bf16_f32 v9, v14, v15
	v_lshlrev_b64 v[14:15], 11, v[4:5]
	v_and_b32_e32 v33, 0xffff0000, v128
	v_mul_f32_e32 v4, 0xbfb8aa3b, v32
	v_exp_f32_e32 v4, v4
	v_mul_f32_e32 v34, 0xbfb8aa3b, v33
	v_exp_f32_e32 v34, v34
	v_lshl_add_u64 v[14:15], v[2:3], 0, v[14:15]
	v_add_f32_e32 v4, 1.0, v4
	global_store_dwordx4 v[14:15], v[6:9], off
	v_lshlrev_b32_e32 v14, 16, v129
	v_and_b32_e32 v15, 0xffff0000, v129
	v_rcp_f32_e32 v6, v4
	v_add_f32_e32 v4, 1.0, v34
	v_rcp_f32_e32 v7, v4
	v_or_b32_e32 v4, s4, v0
	v_mul_f32_e32 v0, 0xbfb8aa3b, v14
	s_waitcnt lgkmcnt(0)
	v_lshlrev_b32_e32 v8, 16, v10
	v_and_b32_e32 v9, 0xffff0000, v10
	v_exp_f32_e32 v0, v0
	v_mul_f32_e32 v10, 0xbfb8aa3b, v15
	v_exp_f32_e32 v10, v10
	v_pk_mul_f32 v[6:7], v[6:7], v[32:33]
	v_add_f32_e32 v0, 1.0, v0
	v_pk_mul_f32 v[6:7], v[6:7], v[8:9]
	v_rcp_f32_e32 v8, v0
	v_add_f32_e32 v0, 1.0, v10
	v_rcp_f32_e32 v9, v0
	v_cvt_pk_bf16_f32 v6, v6, v7
	v_lshlrev_b32_e32 v10, 16, v11
	v_and_b32_e32 v11, 0xffff0000, v11
	v_pk_mul_f32 v[8:9], v[8:9], v[14:15]
	v_lshlrev_b32_e32 v14, 16, v130
	v_and_b32_e32 v15, 0xffff0000, v130
	v_mul_f32_e32 v0, 0xbfb8aa3b, v14
	v_exp_f32_e32 v0, v0
	v_mul_f32_e32 v7, 0xbfb8aa3b, v15
	v_exp_f32_e32 v7, v7
	v_pk_mul_f32 v[8:9], v[8:9], v[10:11]
	v_add_f32_e32 v0, 1.0, v0
	v_rcp_f32_e32 v10, v0
	v_add_f32_e32 v0, 1.0, v7
	v_rcp_f32_e32 v11, v0
	v_cvt_pk_bf16_f32 v7, v8, v9
	v_lshlrev_b32_e32 v8, 16, v12
	v_and_b32_e32 v9, 0xffff0000, v12
	v_pk_mul_f32 v[10:11], v[10:11], v[14:15]
	v_lshlrev_b32_e32 v14, 16, v131
	v_and_b32_e32 v15, 0xffff0000, v131
	v_mul_f32_e32 v0, 0xbfb8aa3b, v14
	v_exp_f32_e32 v0, v0
	v_mul_f32_e32 v12, 0xbfb8aa3b, v15
	v_exp_f32_e32 v12, v12
	v_pk_mul_f32 v[8:9], v[10:11], v[8:9]
	v_add_f32_e32 v0, 1.0, v0
	v_rcp_f32_e32 v10, v0
	v_add_f32_e32 v0, 1.0, v12
	v_rcp_f32_e32 v11, v0
	v_lshlrev_b32_e32 v12, 16, v13
	v_and_b32_e32 v13, 0xffff0000, v13
	v_lshlrev_b64 v[4:5], 11, v[4:5]
	v_pk_mul_f32 v[10:11], v[10:11], v[14:15]
	v_cvt_pk_bf16_f32 v8, v8, v9
	v_pk_mul_f32 v[10:11], v[10:11], v[12:13]
	v_lshl_add_u64 v[2:3], v[2:3], 0, v[4:5]
	v_cvt_pk_bf16_f32 v9, v10, v11
	global_store_dwordx4 v[2:3], v[6:9], off
	s_waitcnt vmcnt(0) lgkmcnt(0)
	s_barrier
	s_mov_b64 s[4:5], 0
.LBB0_1317:
	s_and_b64 vcc, exec, s[4:5]
	s_cbranch_vccz .LBB0_1233
	s_getreg_b32 s4, hwreg(HW_REG_HW_ID, 0, 6)
	s_lshl_b32 s4, s4, 2
	s_and_b32 s4, s4, 0xfc
	s_add_i32 s4, s4, 0
	s_add_i32 s4, s4, 0x256c0
	v_mov_b32_e32 v0, s4
	ds_read_b32 v0, v0
	v_mbcnt_lo_u32_b32 v116, -1, 0
	v_mbcnt_hi_u32_b32 v116, -1, v116
	v_readlane_b32 s20, v254, 8
	v_and_b32_e32 v214, 31, v116
	v_bfe_u32 v215, v116, 5, 1
	s_waitcnt lgkmcnt(0)
	v_readfirstlane_b32 s4, v0
	v_lshlrev_b32_e32 v2, 10, v214
	v_mov_b32_e32 v3, v1
	v_lshl_add_u32 v0, s4, 6, v116
	v_lshlrev_b32_e32 v212, 4, v215
	v_readfirstlane_b32 s8, v0
	s_ashr_i32 s27, s8, 6
	s_lshl_b32 s4, s27, 5
	s_add_i32 s6, s4, s29
	s_ashr_i32 s7, s6, 31
	s_lshl_b64 s[4:5], s[6:7], 10
	s_add_u32 s4, s20, s4
	v_readlane_b32 s20, v254, 35
	s_addc_u32 s5, s20, s5
	s_lshl_b32 s20, s26, 1
	s_add_u32 s20, s4, s20
	s_addc_u32 s21, s5, 0
	v_lshl_add_u64 v[2:3], s[20:21], 0, v[2:3]
	v_mov_b32_e32 v213, v1
	v_readlane_b32 s4, v254, 33
	v_lshl_add_u64 v[2:3], v[2:3], 0, v[212:213]
	s_add_u32 s4, s4, s93
	global_load_dwordx4 v[172:175], v[2:3], off nt
	s_addc_u32 s5, s82, 0
	s_lshl_b32 s31, s28, 1
	s_add_u32 s28, s4, s31
	v_lshrrev_b32_e32 v0, 4, v116
	s_addc_u32 s29, s5, 0
	s_and_b32 s4, s8, 0x3fffffc0
	v_xor_b32_e32 v6, v0, v116
	s_ashr_i32 s8, s8, 8
	v_lshlrev_b32_e32 v0, 6, v116
	s_lshl_b32 s20, s8, 5
	v_lshlrev_b32_e32 v6, 3, v6
	s_and_b32 s5, s27, 3
	v_and_b32_e32 v0, 0xf00, v0
	v_and_or_b32 v6, v6, 24, s20
	v_lshl_or_b32 v0, s5, 12, v0
	v_ashrrev_i32_e32 v7, 31, v6
	v_lshl_add_u64 v[4:5], s[28:29], 0, v[0:1]
	v_lshlrev_b64 v[6:7], 1, v[6:7]
	v_lshl_add_u64 v[200:201], v[4:5], 0, v[6:7]
	v_lshrrev_b32_e32 v4, 2, v116
	v_bitop3_b32 v4, v215, v4, 3 bitop3:0x78
	v_lshlrev_b32_e32 v72, 4, v4
	global_load_dwordx4 v[168:171], v[2:3], off offset:32 nt
	global_load_dwordx4 v[10:13], v[2:3], off offset:64 nt
	s_nop 0
	global_load_dwordx4 v[2:5], v[2:3], off offset:96 nt
	s_ashr_i32 s21, s20, 31
	s_lshl_b32 s42, s8, 12
	s_lshl_b32 s5, s5, 10
	s_lshl_b32 s8, s27, 10
	s_add_u32 s28, s83, s93
	s_addc_u32 s29, s84, 0
	s_add_u32 s28, s28, s31
	s_addc_u32 s29, s29, 0
	v_lshl_add_u64 v[8:9], s[28:29], 0, v[0:1]
	s_lshl_b64 s[28:29], s[20:21], 1
	s_cmp_lg_u32 0, -1
	v_lshlrev_b32_e32 v220, 3, v116
	s_cselect_b32 s20, 0, 0
	v_and_b32_e32 v213, 24, v220
	s_add_i32 s21, s42, s20
	v_lshl_add_u64 v[8:9], v[8:9], 0, s[28:29]
	v_lshlrev_b32_e32 v14, 1, v213
	v_mov_b32_e32 v15, v1
	s_add_i32 s46, s21, s5
	s_add_i32 s5, s20, s8
	s_mov_b32 s20, m0
	s_mov_b32 m0, s46
	s_nop 0
	global_load_lds_dwordx4 v[200:201], off
	s_mov_b32 m0, s20
	v_lshl_add_u64 v[14:15], v[8:9], 0, v[14:15]
	s_add_i32 s47, s5, 0x8000
	s_mov_b32 s20, m0
	s_mov_b32 m0, s47
	s_nop 0
	global_load_lds_dwordx4 v[14:15], off
	s_mov_b32 m0, s20
	s_mov_b64 s[42:43], 0x4000
	v_lshl_add_u64 v[8:9], v[200:201], 0, s[42:43]
	s_add_i32 s20, s46, 0x2000
	s_mov_b32 s21, m0
	s_mov_b32 m0, s20
	s_nop 0
	global_load_lds_dwordx4 v[8:9], off
	s_mov_b32 m0, s21
	v_lshl_add_u64 v[8:9], v[14:15], 0, s[42:43]
	s_add_i32 s20, s5, 0xa000
	s_mov_b32 s21, m0
	s_mov_b32 m0, s20
	s_nop 0
	global_load_lds_dwordx4 v[8:9], off
	s_mov_b32 m0, s21
	v_lshl_add_u32 v73, v214, 6, 0
	v_lshl_add_u64 v[8:9], v[200:201], 0, s[22:23]
	s_add_i32 s20, s46, 0x4000
	s_mov_b32 s21, m0
	s_mov_b32 m0, s20
	s_nop 0
	global_load_lds_dwordx4 v[8:9], off
	s_mov_b32 m0, s21
	v_mov_b32_e32 v32, v1
	v_mov_b32_e32 v33, v1
	v_mov_b32_e32 v34, v1
	v_mov_b32_e32 v35, v1
	v_mov_b32_e32 v36, v1
	v_mov_b32_e32 v37, v1
	v_mov_b32_e32 v38, v1
	v_mov_b32_e32 v39, v1
	v_mov_b32_e32 v40, v1
	v_mov_b32_e32 v41, v1
	v_mov_b32_e32 v42, v1
	v_mov_b32_e32 v43, v1
	v_mov_b32_e32 v44, v1
	v_mov_b32_e32 v45, v1
	v_mov_b32_e32 v46, v1
	v_mov_b32_e32 v47, v1
	v_add_u32_e32 v223, v73, v72
	v_lshl_add_u64 v[8:9], v[200:201], 0, s[24:25]
	s_add_i32 s45, s46, 0x6000
	s_mov_b32 s20, m0
	s_mov_b32 m0, s45
	s_nop 0
	global_load_lds_dwordx4 v[8:9], off
	s_mov_b32 m0, s20
	s_waitcnt vmcnt(5) lgkmcnt(0)
	s_barrier
	ds_read_b128 v[64:67], v223
	ds_read_b128 v[68:71], v223 offset:2048
	s_waitcnt vmcnt(3) lgkmcnt(1)
	v_mfma_f32_32x32x16_bf16 v[48:63], v[64:67], v[172:175], v[32:47]
	v_xad_u32 v224, v72, 32, v73
	v_lshlrev_b32_e32 v8, 1, v116
	v_and_b32_e32 v216, 32, v8
	v_lshlrev_b32_e32 v8, 4, v116
	v_and_b32_e32 v8, 0xc0, v8
	v_lshl_or_b32 v217, v215, 8, v8
	s_lshl_b32 s4, s4, 2
	s_waitcnt lgkmcnt(0)
	v_mfma_f32_32x32x16_bf16 v[32:47], v[68:71], v[172:175], v[32:47]
	ds_read_b128 v[64:67], v224
	ds_read_b128 v[68:71], v224 offset:2048
	s_add_i32 s44, s4, 0
	s_add_i32 s5, s5, 0xc000
	s_add_i32 s44, s44, 0x10000
	s_add_u32 s20, s93, s30
	s_addc_u32 s21, 0, 0
	v_lshl_add_u64 v[6:7], s[20:21], 0, v[6:7]
	s_waitcnt vmcnt(2) lgkmcnt(1)
	v_mfma_f32_32x32x16_bf16 v[48:63], v[64:67], v[168:171], v[48:63]
	v_lshl_add_u64 v[6:7], v[6:7], 0, v[0:1]
	v_lshl_add_u64 v[204:205], s[56:57], 0, v[6:7]
	v_and_b32_e32 v6, 3, v116
	s_add_u32 s20, s28, s20
	v_lshlrev_b32_e32 v6, 4, v6
	v_mov_b32_e32 v7, v1
	s_addc_u32 s21, s29, s21
	s_waitcnt lgkmcnt(0)
	v_mfma_f32_32x32x16_bf16 v[32:47], v[68:71], v[168:171], v[32:47]
	ds_read_b128 v[64:67], v223 offset:4096
	ds_read_b128 v[68:71], v223 offset:6144
	v_lshl_add_u64 v[6:7], s[20:21], 0, v[6:7]
	v_and_b32_e32 v221, 63, v116
	v_add_u32_e32 v117, 0, v216
	v_lshl_add_u64 v[6:7], v[6:7], 0, v[0:1]
	v_mov_b32_e32 v0, 0
	s_mov_b32 s60, -1
	s_waitcnt vmcnt(1) lgkmcnt(1)
	v_mfma_f32_32x32x16_bf16 v[48:63], v[64:67], v[10:13], v[48:63]
	s_mov_b32 s31, 0
	s_movk_i32 s42, 0x2000
	s_movk_i32 s61, 0x4000
	s_movk_i32 s62, 0x6000
	v_add3_u32 v222, v117, v213, v217
	v_lshl_add_u32 v218, v214, 2, s44
	v_lshl_add_u64 v[202:203], v[14:15], 0, s[24:25]
	s_waitcnt lgkmcnt(0)
	v_mfma_f32_32x32x16_bf16 v[32:47], v[68:71], v[10:13], v[32:47]
	ds_read_b128 v[64:67], v224 offset:4096
	ds_read_b128 v[68:71], v224 offset:6144
	v_lshl_add_u64 v[206:207], s[58:59], 0, v[6:7]
	s_waitcnt vmcnt(0) lgkmcnt(1)
	v_mfma_f32_32x32x16_bf16 v[48:63], v[64:67], v[2:5], v[48:63]
	s_waitcnt lgkmcnt(0)
	v_mfma_f32_32x32x16_bf16 v[32:47], v[68:71], v[2:5], v[32:47]
	s_nop 15
	s_nop 7
	s_nop 0
	v_max3_f32 v8, v48, v49, v32
	v_max3_f32 v9, v50, v51, v33
	s_nop 0
	v_max3_f32 v8, v8, v34, v35
	v_max3_f32 v9, v9, v54, v55
	s_nop 0
	v_max3_f32 v8, v8, v52, v53
	v_max3_f32 v9, v9, v38, v39
	s_nop 0
	v_max3_f32 v8, v8, v36, v37
	v_max3_f32 v9, v9, v58, v59
	s_nop 0
	v_max3_f32 v8, v8, v56, v57
	v_max3_f32 v9, v9, v42, v43
	s_nop 0
	v_max3_f32 v8, v8, v40, v41
	v_max3_f32 v9, v9, v62, v63
	s_nop 0
	v_max3_f32 v8, v8, v60, v61
	v_max3_f32 v9, v9, v46, v47
	s_nop 0
	v_max3_f32 v8, v8, v44, v45
	s_nop 0
	v_max_f32_e32 v8, v8, v9
	s_nop 0
	v_mov_b32_e32 v9, v8
	s_nop 1
	v_permlane32_swap_b32_e32 v8, v9
	v_max_f32_e32 v8, v8, v9
	s_nop 0
	v_add_f32_e32 v219, v1, v8
	v_sub_f32_e32 v9, v48, v8
	v_sub_f32_e32 v32, v32, v8
	v_sub_f32_e32 v48, v49, v8
	v_sub_f32_e32 v33, v33, v8
	v_sub_f32_e32 v49, v50, v8
	s_nop 0
	v_xor_b32_e32 v64, 0x80000000, v219
	v_mov_b32_e32 v65, v64
	v_mov_b32_e32 v66, v64
	v_mov_b32_e32 v67, v64
	v_mov_b32_e32 v68, v64
	v_mov_b32_e32 v69, v64
	v_mov_b32_e32 v70, v64
	v_mov_b32_e32 v71, v64
	v_mov_b32_e32 v72, v64
	v_mov_b32_e32 v73, v64
	v_mov_b32_e32 v74, v64
	v_mov_b32_e32 v75, v64
	v_mov_b32_e32 v76, v64
	v_mov_b32_e32 v77, v64
	v_mov_b32_e32 v78, v64
	v_mov_b32_e32 v79, v64
	v_sub_f32_e32 v34, v34, v8
	v_sub_f32_e32 v50, v51, v8
	v_sub_f32_e32 v35, v35, v8
	v_sub_f32_e32 v51, v52, v8
	v_sub_f32_e32 v36, v36, v8
	v_sub_f32_e32 v52, v53, v8
	v_sub_f32_e32 v37, v37, v8
	v_sub_f32_e32 v53, v54, v8
	v_sub_f32_e32 v38, v38, v8
	v_sub_f32_e32 v54, v55, v8
	v_sub_f32_e32 v39, v39, v8
	v_sub_f32_e32 v55, v56, v8
	v_sub_f32_e32 v40, v40, v8
	v_sub_f32_e32 v56, v57, v8
	v_sub_f32_e32 v41, v41, v8
	v_sub_f32_e32 v57, v58, v8
	v_sub_f32_e32 v42, v42, v8
	v_sub_f32_e32 v58, v59, v8
	v_sub_f32_e32 v43, v43, v8
	v_sub_f32_e32 v59, v60, v8
	v_sub_f32_e32 v44, v44, v8
	v_sub_f32_e32 v60, v61, v8
	v_sub_f32_e32 v45, v45, v8
	v_sub_f32_e32 v61, v62, v8
	v_sub_f32_e32 v46, v46, v8
	v_sub_f32_e32 v62, v63, v8
	v_sub_f32_e32 v8, v47, v8
	s_waitcnt vmcnt(3) lgkmcnt(0)
	s_barrier
	v_exp_f32_e32 v96, v9
	v_exp_f32_e32 v95, v8
	v_lshl_add_u64 v[8:9], v[200:201], 0, s[14:15]
	s_mov_b32 s4, m0
	s_mov_b32 m0, s46
	s_nop 0
	global_load_lds_dwordx4 v[8:9], off
	s_mov_b32 m0, s4
	v_lshl_add_u64 v[8:9], v[14:15], 0, s[22:23]
	s_mov_b32 s4, m0
	s_mov_b32 m0, s5
	s_nop 0
	global_load_lds_dwordx4 v[8:9], off
	s_mov_b32 m0, s4
	ds_read_b128 v[112:115], v223 offset:8192
	ds_read_b128 v[188:191], v223 offset:10240
	ds_read_b128 v[184:187], v224 offset:8192
	ds_read_b128 v[180:183], v224 offset:10240
	ds_read_b128 v[156:159], v223 offset:12288
	ds_read_b128 v[152:155], v223 offset:14336
	ds_read_b128 v[148:151], v224 offset:12288
	ds_read_b128 v[144:147], v224 offset:14336
	v_exp_f32_e32 v97, v48
	v_exp_f32_e32 v98, v49
	v_exp_f32_e32 v99, v50
	v_exp_f32_e32 v100, v51
	v_exp_f32_e32 v101, v52
	v_exp_f32_e32 v102, v53
	v_exp_f32_e32 v103, v54
	v_exp_f32_e32 v104, v55
	v_exp_f32_e32 v105, v56
	v_exp_f32_e32 v106, v57
	v_exp_f32_e32 v107, v58
	v_exp_f32_e32 v108, v59
	v_exp_f32_e32 v109, v60
	v_exp_f32_e32 v110, v61
	v_exp_f32_e32 v111, v62
	v_exp_f32_e32 v80, v32
	v_exp_f32_e32 v81, v33
	v_exp_f32_e32 v82, v34
	v_exp_f32_e32 v83, v35
	v_exp_f32_e32 v84, v36
	v_exp_f32_e32 v85, v37
	v_exp_f32_e32 v86, v38
	v_exp_f32_e32 v87, v39
	v_exp_f32_e32 v88, v40
	v_exp_f32_e32 v89, v41
	v_exp_f32_e32 v90, v42
	v_exp_f32_e32 v91, v43
	v_exp_f32_e32 v92, v44
	v_exp_f32_e32 v93, v45
	v_exp_f32_e32 v94, v46
	s_waitcnt vmcnt(3) lgkmcnt(0)
	s_barrier
	v_cmp_gt_u32_e64 s[4:5], 32, v221
	v_mov_b32_e32 v32, 0
	v_mov_b32_e32 v33, v0
	v_mov_b32_e32 v34, v0
	v_mov_b32_e32 v35, v0
	v_mov_b32_e32 v36, v0
	v_mov_b32_e32 v37, v0
	v_mov_b32_e32 v38, v0
	v_mov_b32_e32 v39, v0
	v_mov_b32_e32 v40, v0
	v_mov_b32_e32 v41, v0
	v_mov_b32_e32 v42, v0
	v_mov_b32_e32 v43, v0
	v_mov_b32_e32 v44, v0
	v_mov_b32_e32 v45, v0
	v_mov_b32_e32 v46, v0
	v_mov_b32_e32 v47, v0
	v_mov_b32_e32 v48, 0
	v_mov_b32_e32 v49, v0
	v_mov_b32_e32 v50, v0
	v_mov_b32_e32 v51, v0
	v_mov_b32_e32 v52, v0
	v_mov_b32_e32 v53, v0
	v_mov_b32_e32 v54, v0
	v_mov_b32_e32 v55, v0
	v_mov_b32_e32 v56, v0
	v_mov_b32_e32 v57, v0
	v_mov_b32_e32 v58, v0
	v_mov_b32_e32 v59, v0
	v_mov_b32_e32 v60, v0
	v_mov_b32_e32 v61, v0
	v_mov_b32_e32 v62, v0
	v_mov_b32_e32 v63, v0

.LBB0_1351:
	v_lshrrev_b32_e32 v200, 3, v221
	v_or_b32_e32 v6, s6, v200
	v_mov_b32_e32 v7, s7
	v_lshlrev_b64 v[14:15], 11, v[6:7]
	v_lshl_add_u64 v[6:7], s[48:49], 0, v[14:15]
	s_lshl_b32 s8, s26, 1
	v_and_b32_e32 v0, 56, v220
	v_lshl_add_u64 v[6:7], v[6:7], 0, s[8:9]
	v_lshlrev_b32_e32 v0, 1, v0
	v_lshl_add_u64 v[6:7], v[6:7], 0, v[0:1]
	v_add_co_u32_e32 v96, vcc, s67, v6
	s_nop 1
	v_addc_co_u32_e32 v97, vcc, 0, v7, vcc
	global_load_dwordx4 v[140:143], v[6:7], off nt
	global_load_dwordx4 v[136:139], v[96:97], off nt
	v_add_co_u32_e32 v96, vcc, s66, v6
	s_nop 1
	v_addc_co_u32_e32 v97, vcc, 0, v7, vcc
	v_add_co_u32_e32 v6, vcc, s63, v6
	s_nop 1
	v_addc_co_u32_e32 v7, vcc, 0, v7, vcc
	global_load_dwordx4 v[132:135], v[96:97], off nt
	global_load_dwordx4 v[128:131], v[6:7], off nt
	ds_read_b64_tr_b16 v[148:149], v222 offset:49152
	ds_read_b64_tr_b16 v[150:151], v222 offset:49664
	s_waitcnt lgkmcnt(9)
	v_mfma_f32_32x32x16_bf16 v[96:111], v[196:199], v[172:175], v[64:79]
	v_add_f32_e32 v250, v112, v113
	v_add_f32_e32 v251, v114, v115
	v_add_f32_e32 v252, v116, v117
	v_add_f32_e32 v253, v118, v119
	v_add_f32_e32 v250, v120, v250
	v_cvt_pk_bf16_f32 v176, v112, v113
	v_cvt_pk_bf16_f32 v177, v114, v115
	ds_read_b64_tr_b16 v[112:113], v222 offset:53248
	ds_read_b64_tr_b16 v[114:115], v222 offset:53760
	s_waitcnt lgkmcnt(10)
	v_mfma_f32_32x32x16_bf16 v[64:79], v[192:195], v[172:175], v[64:79]
	v_add_f32_e32 v251, v121, v251
	v_add_f32_e32 v252, v122, v252
	v_add_f32_e32 v253, v123, v253
	v_add_f32_e32 v250, v124, v250
	v_cvt_pk_bf16_f32 v178, v116, v117
	v_cvt_pk_bf16_f32 v179, v118, v119
	ds_read_b64_tr_b16 v[116:117], v222 offset:50176
	ds_read_b64_tr_b16 v[118:119], v222 offset:50688
	s_waitcnt lgkmcnt(11)
	v_mfma_f32_32x32x16_bf16 v[96:111], v[188:191], v[168:171], v[96:111]
	v_add_f32_e32 v251, v125, v251
	v_add_f32_e32 v252, v126, v252
	v_add_f32_e32 v253, v127, v253
	v_add_f32_e32 v250, v80, v250
	v_cvt_pk_bf16_f32 v164, v120, v121
	v_cvt_pk_bf16_f32 v165, v122, v123
	ds_read_b64_tr_b16 v[120:121], v222 offset:54272
	ds_read_b64_tr_b16 v[122:123], v222 offset:54784
	s_waitcnt lgkmcnt(12)
	v_mfma_f32_32x32x16_bf16 v[64:79], v[184:187], v[168:171], v[64:79]
	v_add_f32_e32 v251, v81, v251
	v_add_f32_e32 v252, v82, v252
	v_add_f32_e32 v253, v83, v253
	v_add_f32_e32 v250, v84, v250
	v_cvt_pk_bf16_f32 v166, v124, v125
	v_cvt_pk_bf16_f32 v167, v126, v127
	ds_read_b64_tr_b16 v[124:125], v222 offset:51200
	ds_read_b64_tr_b16 v[126:127], v222 offset:51712
	s_waitcnt lgkmcnt(13)
	v_mfma_f32_32x32x16_bf16 v[96:111], v[180:183], v[10:13], v[96:111]
	v_add_f32_e32 v251, v85, v251
	v_add_f32_e32 v252, v86, v252
	v_add_f32_e32 v253, v87, v253
	v_add_f32_e32 v250, v88, v250
	v_cvt_pk_bf16_f32 v160, v80, v81
	v_cvt_pk_bf16_f32 v161, v82, v83
	ds_read_b64_tr_b16 v[168:169], v222 offset:55296
	ds_read_b64_tr_b16 v[170:171], v222 offset:55808
	s_waitcnt lgkmcnt(14)
	v_mfma_f32_32x32x16_bf16 v[64:79], v[156:159], v[10:13], v[64:79]
	v_add_f32_e32 v251, v89, v251
	v_add_f32_e32 v252, v90, v252
	v_add_f32_e32 v253, v91, v253
	v_add_f32_e32 v250, v92, v250
	v_cvt_pk_bf16_f32 v162, v84, v85
	v_cvt_pk_bf16_f32 v163, v86, v87
	ds_read_b64_tr_b16 v[10:11], v222 offset:52224
	ds_read_b64_tr_b16 v[12:13], v222 offset:52736
	s_waitcnt lgkmcnt(14)
	v_mfma_f32_32x32x16_bf16 v[96:111], v[152:155], v[2:5], v[96:111]
	v_add_f32_e32 v251, v93, v251
	v_add_f32_e32 v252, v94, v252
	v_add_f32_e32 v253, v95, v253
	v_add_f32_e32 v250, v251, v250
	v_cvt_pk_bf16_f32 v6, v88, v89
	v_cvt_pk_bf16_f32 v7, v90, v91
	ds_read_b64_tr_b16 v[152:153], v222 offset:56320
	ds_read_b64_tr_b16 v[154:155], v222 offset:56832
	v_mfma_f32_32x32x16_bf16 v[64:79], v[144:147], v[2:5], v[64:79]
	v_add_f32_e32 v252, v253, v252
	v_add_f32_e32 v80, v252, v250
	v_cvt_pk_bf16_f32 v8, v92, v93
	v_cvt_pk_bf16_f32 v9, v94, v95
	v_max_f32_e32 v2, v96, v96
	v_max_f32_e32 v2, 0xff800000, v2
	v_max3_f32 v3, v98, s69, v99
	s_nop 4
	v_max3_f32 v2, v2, v97, v64
	v_max3_f32 v3, v3, v66, v67
	v_max3_f32 v2, v2, v65, v100
	v_max3_f32 v3, v3, v102, v103
	v_max3_f32 v2, v2, v101, v68
	v_max3_f32 v3, v3, v70, v71
	v_max3_f32 v2, v2, v69, v104
	v_max3_f32 v3, v3, v106, v107
	v_max3_f32 v2, v2, v105, v72
	v_max3_f32 v3, v3, v74, v75
	v_max3_f32 v2, v2, v73, v108
	v_max3_f32 v3, v3, v110, v111
	v_max3_f32 v4, v2, v109, v76
	v_max3_f32 v3, v3, v78, v79
	v_max3_f32 v3, v4, v77, v3
	v_mov_b32_e32 v4, v3
	s_nop 1
	v_permlane32_swap_b32_e32 v3, v4
	v_max3_f32 v3, v3, s69, v4
	v_cmp_lt_f32_e32 vcc, s72, v3
	s_cmp_lg_u64 vcc, 0
	v_add_f32_e32 v2, v201, v80
	s_cselect_b64 s[28:29], -1, 0
	s_cbranch_vccnz .LBB0_1383
